# K-loop LDS-DMA loads use SGPR-base + 32-bit VGPR offset addressing (drops 16 64-bit VALU adds per iteration) in in_proj/ffn_in/down loops
# speedup vs baseline: 1.0149x; 1.0044x over previous
.Lpeel_p1:
	ds_read_b128 v[130:133], v173
	ds_read_b128 v[134:137], v173 offset:1024
	ds_read_b128 v[138:141], v173 offset:2048
	ds_read_b128 v[142:145], v173 offset:3072
	s_add_u32 s6, s2, 0xfffc0080
	s_addc_u32 s7, s3, -1
	s_cmp_eq_u32 s73, 12
	s_cselect_b32 s9, s1, s7
	s_cselect_b32 s8, s33, s6
	s_cselect_b32 s7, s39, s72
	s_cselect_b32 s6, s41, s71
	s_add_i32 m0, s50, 0xc000
	ds_read_b128 v[180:183], v175
	ds_read_b128 v[184:187], v175 offset:1024
	ds_read_b128 v[190:193], v175 offset:2048
	ds_read_b128 v[194:197], v175 offset:3072
	ds_read_b128 v[198:201], v175 offset:4096
	ds_read_b128 v[202:205], v175 offset:5120
	ds_read_b128 v[206:209], v175 offset:6144
	ds_read_b128 v[210:213], v175 offset:7168
	global_load_lds_dwordx4 v156, s[2:3]
	s_add_i32 m0, s50, 0xe000
	s_nop 0
	global_load_lds_dwordx4 v158, s[2:3]
	s_waitcnt lgkmcnt(8)
	s_barrier
	s_waitcnt lgkmcnt(0)
	s_setprio 1
	s_waitcnt lgkmcnt(0)
	v_mfma_f32_16x16x32_bf16 v[126:129], v[130:133], v[180:183], 0
	v_mfma_f32_16x16x32_bf16 v[122:125], v[138:141], v[180:183], 0
	v_mfma_f32_16x16x32_bf16 v[118:121], v[130:133], v[190:193], 0
	v_mfma_f32_16x16x32_bf16 v[110:113], v[138:141], v[190:193], 0
	v_mfma_f32_16x16x32_bf16 v[102:105], v[130:133], v[198:201], 0
	v_mfma_f32_16x16x32_bf16 v[94:97], v[138:141], v[198:201], 0
	v_mfma_f32_16x16x32_bf16 v[86:89], v[130:133], v[206:209], 0
	v_mfma_f32_16x16x32_bf16 v[78:81], v[138:141], v[206:209], 0
	v_mfma_f32_16x16x32_bf16 v[126:129], v[134:137], v[184:187], v[126:129]
	v_mfma_f32_16x16x32_bf16 v[122:125], v[142:145], v[184:187], v[122:125]
	v_mfma_f32_16x16x32_bf16 v[118:121], v[134:137], v[194:197], v[118:121]
	v_mfma_f32_16x16x32_bf16 v[110:113], v[142:145], v[194:197], v[110:113]
	v_mfma_f32_16x16x32_bf16 v[102:105], v[134:137], v[202:205], v[102:105]
	v_mfma_f32_16x16x32_bf16 v[94:97], v[142:145], v[202:205], v[94:97]
	v_mfma_f32_16x16x32_bf16 v[86:89], v[134:137], v[210:213], v[86:89]
	v_mfma_f32_16x16x32_bf16 v[78:81], v[142:145], v[210:213], v[78:81]
	s_setprio 0
	s_barrier
	s_add_i32 s74, s66, s49
	s_add_u32 s98, s6, 0x80
	s_addc_u32 s99, s7, 0
	s_mov_b32 m0, s74
	ds_read_b128 v[214:217], v177
	ds_read_b128 v[218:221], v177 offset:1024
	ds_read_b128 v[222:225], v177 offset:2048
	ds_read_b128 v[226:229], v177 offset:3072
	global_load_lds_dwordx4 v148, s[6:7]
	s_add_i32 m0, s74, 0x2000
	s_nop 0
	global_load_lds_dwordx4 v152, s[6:7]
	s_barrier
	s_waitcnt lgkmcnt(0)
	s_setprio 1
	s_waitcnt lgkmcnt(0)
	v_mfma_f32_16x16x32_bf16 v[114:117], v[214:217], v[180:183], 0
	v_mfma_f32_16x16x32_bf16 v[106:109], v[222:225], v[180:183], 0
	v_mfma_f32_16x16x32_bf16 v[98:101], v[214:217], v[190:193], 0
	v_mfma_f32_16x16x32_bf16 v[90:93], v[222:225], v[190:193], 0
	v_mfma_f32_16x16x32_bf16 v[82:85], v[214:217], v[198:201], 0
	v_mfma_f32_16x16x32_bf16 v[74:77], v[222:225], v[198:201], 0
	v_mfma_f32_16x16x32_bf16 v[70:73], v[214:217], v[206:209], 0
	v_mfma_f32_16x16x32_bf16 v[66:69], v[222:225], v[206:209], 0
	v_mfma_f32_16x16x32_bf16 v[114:117], v[218:221], v[184:187], v[114:117]
	v_mfma_f32_16x16x32_bf16 v[106:109], v[226:229], v[184:187], v[106:109]
	v_mfma_f32_16x16x32_bf16 v[98:101], v[218:221], v[194:197], v[98:101]
	v_mfma_f32_16x16x32_bf16 v[90:93], v[226:229], v[194:197], v[90:93]
	v_mfma_f32_16x16x32_bf16 v[82:85], v[218:221], v[202:205], v[82:85]
	v_mfma_f32_16x16x32_bf16 v[74:77], v[226:229], v[202:205], v[74:77]
	v_mfma_f32_16x16x32_bf16 v[70:73], v[218:221], v[210:213], v[70:73]
	v_mfma_f32_16x16x32_bf16 v[66:69], v[226:229], v[210:213], v[66:69]
	s_setprio 0
	s_mov_b32 m0, s50
	s_add_u32 s100, s8, 0x80
	s_addc_u32 s101, s9, 0
	s_barrier
	ds_read_b128 v[180:183], v175 offset:16384
	ds_read_b128 v[184:187], v175 offset:17408
	ds_read_b128 v[190:193], v175 offset:18432
	ds_read_b128 v[194:197], v175 offset:19456
	ds_read_b128 v[198:201], v175 offset:20480
	ds_read_b128 v[202:205], v175 offset:21504
	ds_read_b128 v[206:209], v175 offset:22528
	ds_read_b128 v[210:213], v175 offset:23552
	global_load_lds_dwordx4 v146, s[8:9]
	s_mov_b32 m0, s51
	s_nop 0
	global_load_lds_dwordx4 v150, s[8:9]
	s_barrier
	s_waitcnt lgkmcnt(0)
	s_setprio 1
	s_waitcnt lgkmcnt(0)
	v_mfma_f32_16x16x32_bf16 v[62:65], v[130:133], v[180:183], 0
	v_mfma_f32_16x16x32_bf16 v[58:61], v[138:141], v[180:183], 0
	v_mfma_f32_16x16x32_bf16 v[54:57], v[130:133], v[190:193], 0
	v_mfma_f32_16x16x32_bf16 v[46:49], v[138:141], v[190:193], 0
	v_mfma_f32_16x16x32_bf16 v[38:41], v[130:133], v[198:201], 0
	v_mfma_f32_16x16x32_bf16 v[30:33], v[138:141], v[198:201], 0
	v_mfma_f32_16x16x32_bf16 v[22:25], v[130:133], v[206:209], 0
	v_mfma_f32_16x16x32_bf16 v[14:17], v[138:141], v[206:209], 0
	v_mfma_f32_16x16x32_bf16 v[62:65], v[134:137], v[184:187], v[62:65]
	v_mfma_f32_16x16x32_bf16 v[58:61], v[142:145], v[184:187], v[58:61]
	v_mfma_f32_16x16x32_bf16 v[54:57], v[134:137], v[194:197], v[54:57]
	v_mfma_f32_16x16x32_bf16 v[46:49], v[142:145], v[194:197], v[46:49]
	v_mfma_f32_16x16x32_bf16 v[38:41], v[134:137], v[202:205], v[38:41]
	v_mfma_f32_16x16x32_bf16 v[30:33], v[142:145], v[202:205], v[30:33]
	v_mfma_f32_16x16x32_bf16 v[22:25], v[134:137], v[210:213], v[22:25]
	v_mfma_f32_16x16x32_bf16 v[14:17], v[142:145], v[210:213], v[14:17]
	s_setprio 0
	s_barrier
	s_add_u32 s74, s6, 0x40000
	s_addc_u32 s75, s7, 0
	s_add_i32 s76, s67, s49
	s_mov_b32 m0, s76
	s_nop 0
	global_load_lds_dwordx4 v148, s[74:75]
	s_add_i32 m0, s76, 0x2000
	s_nop 0
	global_load_lds_dwordx4 v152, s[74:75]
	s_waitcnt vmcnt(6)
	s_barrier
	s_setprio 1
	v_mfma_f32_16x16x32_bf16 v[50:53], v[214:217], v[180:183], 0
	v_mfma_f32_16x16x32_bf16 v[42:45], v[222:225], v[180:183], 0
	v_mfma_f32_16x16x32_bf16 v[34:37], v[214:217], v[190:193], 0
	v_mfma_f32_16x16x32_bf16 v[26:29], v[222:225], v[190:193], 0
	v_mfma_f32_16x16x32_bf16 v[18:21], v[214:217], v[198:201], 0
	v_mfma_f32_16x16x32_bf16 v[10:13], v[222:225], v[198:201], 0
	v_mfma_f32_16x16x32_bf16 v[6:9], v[214:217], v[206:209], 0
	v_mfma_f32_16x16x32_bf16 v[2:5], v[222:225], v[206:209], 0
	v_mfma_f32_16x16x32_bf16 v[50:53], v[218:221], v[184:187], v[50:53]
	v_mfma_f32_16x16x32_bf16 v[42:45], v[226:229], v[184:187], v[42:45]
	v_mfma_f32_16x16x32_bf16 v[34:37], v[218:221], v[194:197], v[34:37]
	v_mfma_f32_16x16x32_bf16 v[26:29], v[226:229], v[194:197], v[26:29]
	v_mfma_f32_16x16x32_bf16 v[18:21], v[218:221], v[202:205], v[18:21]
	v_mfma_f32_16x16x32_bf16 v[10:13], v[226:229], v[202:205], v[10:13]
	v_mfma_f32_16x16x32_bf16 v[6:9], v[218:221], v[210:213], v[6:9]
	v_mfma_f32_16x16x32_bf16 v[2:5], v[226:229], v[210:213], v[2:5]
	s_setprio 0
	s_add_i32 s74, 0, 0x18000
	v_add_u32_e32 v142, s74, v171
	s_barrier
	ds_read_b128 v[130:133], v142
	ds_read_b128 v[134:137], v142 offset:1024
	ds_read_b128 v[138:141], v142 offset:2048
	ds_read_b128 v[142:145], v142 offset:3072
	s_add_u32 s8, s8, 0x40000
	s_addc_u32 s9, s9, 0
	s_mov_b32 m0, s52
	ds_read_b128 v[180:183], v175 offset:32768
	ds_read_b128 v[184:187], v175 offset:33792
	ds_read_b128 v[190:193], v175 offset:34816
	ds_read_b128 v[194:197], v175 offset:35840
	ds_read_b128 v[198:201], v175 offset:36864
	ds_read_b128 v[202:205], v175 offset:37888
	ds_read_b128 v[206:209], v175 offset:38912
	ds_read_b128 v[210:213], v175 offset:39936
	global_load_lds_dwordx4 v146, s[8:9]
	s_mov_b32 m0, s53
	s_nop 0
	global_load_lds_dwordx4 v150, s[8:9]
	s_waitcnt lgkmcnt(8)
	s_barrier
	s_waitcnt lgkmcnt(0)
	s_setprio 1
	s_waitcnt lgkmcnt(0)
	v_mfma_f32_16x16x32_bf16 v[126:129], v[130:133], v[180:183], v[126:129]
	v_mfma_f32_16x16x32_bf16 v[122:125], v[138:141], v[180:183], v[122:125]
	v_mfma_f32_16x16x32_bf16 v[118:121], v[130:133], v[190:193], v[118:121]
	v_mfma_f32_16x16x32_bf16 v[110:113], v[138:141], v[190:193], v[110:113]
	v_mfma_f32_16x16x32_bf16 v[102:105], v[130:133], v[198:201], v[102:105]
	v_mfma_f32_16x16x32_bf16 v[94:97], v[138:141], v[198:201], v[94:97]
	v_mfma_f32_16x16x32_bf16 v[86:89], v[130:133], v[206:209], v[86:89]
	v_mfma_f32_16x16x32_bf16 v[78:81], v[138:141], v[206:209], v[78:81]
	v_mfma_f32_16x16x32_bf16 v[126:129], v[134:137], v[184:187], v[126:129]
	v_mfma_f32_16x16x32_bf16 v[122:125], v[142:145], v[184:187], v[122:125]
	v_mfma_f32_16x16x32_bf16 v[118:121], v[134:137], v[194:197], v[118:121]
	v_mfma_f32_16x16x32_bf16 v[110:113], v[142:145], v[194:197], v[110:113]
	v_mfma_f32_16x16x32_bf16 v[102:105], v[134:137], v[202:205], v[102:105]
	v_mfma_f32_16x16x32_bf16 v[94:97], v[142:145], v[202:205], v[94:97]
	v_mfma_f32_16x16x32_bf16 v[86:89], v[134:137], v[210:213], v[86:89]
	v_mfma_f32_16x16x32_bf16 v[78:81], v[142:145], v[210:213], v[78:81]
	s_setprio 0
	s_barrier
	s_add_i32 s8, 0, 0x1c000
	s_add_i32 s9, s74, s49
	v_add_u32_e32 v154, s8, v171
	s_mov_b32 m0, s9
	ds_read_b128 v[214:217], v154
	ds_read_b128 v[218:221], v154 offset:1024
	ds_read_b128 v[222:225], v154 offset:2048
	ds_read_b128 v[226:229], v154 offset:3072
	global_load_lds_dwordx4 v148, s[98:99]
	s_add_i32 m0, s9, 0x2000
	s_nop 0
	global_load_lds_dwordx4 v152, s[98:99]
	s_barrier
	s_waitcnt lgkmcnt(0)
	s_setprio 1
	s_waitcnt lgkmcnt(0)
	v_mfma_f32_16x16x32_bf16 v[114:117], v[214:217], v[180:183], v[114:117]
	v_mfma_f32_16x16x32_bf16 v[106:109], v[222:225], v[180:183], v[106:109]
	v_mfma_f32_16x16x32_bf16 v[98:101], v[214:217], v[190:193], v[98:101]
	v_mfma_f32_16x16x32_bf16 v[90:93], v[222:225], v[190:193], v[90:93]
	v_mfma_f32_16x16x32_bf16 v[82:85], v[214:217], v[198:201], v[82:85]
	v_mfma_f32_16x16x32_bf16 v[74:77], v[222:225], v[198:201], v[74:77]
	v_mfma_f32_16x16x32_bf16 v[70:73], v[214:217], v[206:209], v[70:73]
	v_mfma_f32_16x16x32_bf16 v[66:69], v[222:225], v[206:209], v[66:69]
	v_mfma_f32_16x16x32_bf16 v[114:117], v[218:221], v[184:187], v[114:117]
	v_mfma_f32_16x16x32_bf16 v[106:109], v[226:229], v[184:187], v[106:109]
	v_mfma_f32_16x16x32_bf16 v[98:101], v[218:221], v[194:197], v[98:101]
	v_mfma_f32_16x16x32_bf16 v[90:93], v[226:229], v[194:197], v[90:93]
	v_mfma_f32_16x16x32_bf16 v[82:85], v[218:221], v[202:205], v[82:85]
	v_mfma_f32_16x16x32_bf16 v[74:77], v[226:229], v[202:205], v[74:77]
	v_mfma_f32_16x16x32_bf16 v[70:73], v[218:221], v[210:213], v[70:73]
	v_mfma_f32_16x16x32_bf16 v[66:69], v[226:229], v[210:213], v[66:69]
	s_setprio 0
	s_mov_b32 m0, s56
	s_barrier
	ds_read_b128 v[180:183], v175 offset:49152
	ds_read_b128 v[184:187], v175 offset:50176
	ds_read_b128 v[190:193], v175 offset:51200
	ds_read_b128 v[194:197], v175 offset:52224
	ds_read_b128 v[198:201], v175 offset:53248
	ds_read_b128 v[202:205], v175 offset:54272
	ds_read_b128 v[206:209], v175 offset:55296
	ds_read_b128 v[210:213], v175 offset:56320
	global_load_lds_dwordx4 v146, s[100:101]
	s_mov_b32 m0, s57
	s_nop 0
	global_load_lds_dwordx4 v150, s[100:101]
	s_barrier
	s_waitcnt lgkmcnt(0)
	s_setprio 1
	s_waitcnt lgkmcnt(0)
	v_mfma_f32_16x16x32_bf16 v[62:65], v[130:133], v[180:183], v[62:65]
	v_mfma_f32_16x16x32_bf16 v[58:61], v[138:141], v[180:183], v[58:61]
	v_mfma_f32_16x16x32_bf16 v[54:57], v[130:133], v[190:193], v[54:57]
	v_mfma_f32_16x16x32_bf16 v[46:49], v[138:141], v[190:193], v[46:49]
	v_mfma_f32_16x16x32_bf16 v[38:41], v[130:133], v[198:201], v[38:41]
	v_mfma_f32_16x16x32_bf16 v[30:33], v[138:141], v[198:201], v[30:33]
	v_mfma_f32_16x16x32_bf16 v[22:25], v[130:133], v[206:209], v[22:25]
	v_mfma_f32_16x16x32_bf16 v[14:17], v[138:141], v[206:209], v[14:17]
	v_mfma_f32_16x16x32_bf16 v[62:65], v[134:137], v[184:187], v[62:65]
	v_mfma_f32_16x16x32_bf16 v[58:61], v[142:145], v[184:187], v[58:61]
	v_mfma_f32_16x16x32_bf16 v[54:57], v[134:137], v[194:197], v[54:57]
	v_mfma_f32_16x16x32_bf16 v[46:49], v[142:145], v[194:197], v[46:49]
	v_mfma_f32_16x16x32_bf16 v[38:41], v[134:137], v[202:205], v[38:41]
	v_mfma_f32_16x16x32_bf16 v[30:33], v[142:145], v[202:205], v[30:33]
	v_mfma_f32_16x16x32_bf16 v[22:25], v[134:137], v[210:213], v[22:25]
	v_mfma_f32_16x16x32_bf16 v[14:17], v[142:145], v[210:213], v[14:17]
	s_setprio 0
	s_barrier
	s_add_u32 s6, s6, 0x40080
	s_addc_u32 s7, s7, 0
	s_add_i32 s8, s8, s49
	s_mov_b32 m0, s8
	s_nop 0
	global_load_lds_dwordx4 v148, s[6:7]
	s_add_i32 m0, s8, 0x2000
	s_nop 0
	global_load_lds_dwordx4 v152, s[6:7]
	s_waitcnt vmcnt(6)
	s_barrier
	s_setprio 1
	v_mfma_f32_16x16x32_bf16 v[50:53], v[214:217], v[180:183], v[50:53]
	v_mfma_f32_16x16x32_bf16 v[42:45], v[222:225], v[180:183], v[42:45]
	v_mfma_f32_16x16x32_bf16 v[34:37], v[214:217], v[190:193], v[34:37]
	v_mfma_f32_16x16x32_bf16 v[26:29], v[222:225], v[190:193], v[26:29]
	v_mfma_f32_16x16x32_bf16 v[18:21], v[214:217], v[198:201], v[18:21]
	v_mfma_f32_16x16x32_bf16 v[10:13], v[222:225], v[198:201], v[10:13]
	v_mfma_f32_16x16x32_bf16 v[6:9], v[214:217], v[206:209], v[6:9]
	v_mfma_f32_16x16x32_bf16 v[2:5], v[222:225], v[206:209], v[2:5]
	v_mfma_f32_16x16x32_bf16 v[50:53], v[218:221], v[184:187], v[50:53]
	v_mfma_f32_16x16x32_bf16 v[42:45], v[226:229], v[184:187], v[42:45]
	v_mfma_f32_16x16x32_bf16 v[34:37], v[218:221], v[194:197], v[34:37]
	v_mfma_f32_16x16x32_bf16 v[26:29], v[226:229], v[194:197], v[26:29]
	v_mfma_f32_16x16x32_bf16 v[18:21], v[218:221], v[202:205], v[18:21]
	v_mfma_f32_16x16x32_bf16 v[10:13], v[226:229], v[202:205], v[10:13]
	v_mfma_f32_16x16x32_bf16 v[6:9], v[218:221], v[210:213], v[6:9]
	v_mfma_f32_16x16x32_bf16 v[2:5], v[226:229], v[210:213], v[2:5]
	s_setprio 0
	s_add_i32 s73, s73, 2
	s_add_u32 s2, s2, 0x100
	s_addc_u32 s3, s3, 0
	s_add_u32 s71, s71, 0x100
	s_addc_u32 s72, s72, 0
	s_cmp_gt_u32 s73, 13
	s_barrier
	s_cbranch_scc1 .Lpeel_p1_exit
.LBB0_212:
	ds_read_b128 v[130:133], v173
	ds_read_b128 v[134:137], v173 offset:1024
	ds_read_b128 v[138:141], v173 offset:2048
	ds_read_b128 v[142:145], v173 offset:3072
	s_add_u32 s6, s2, 0xfffc0080
	s_addc_u32 s7, s3, -1
	s_cmp_eq_u32 s73, 12
	s_cselect_b32 s9, s1, s7
	s_cselect_b32 s8, s33, s6
	s_cselect_b32 s7, s39, s72
	s_cselect_b32 s6, s41, s71
	s_add_i32 m0, s50, 0xc000
	ds_read_b128 v[180:183], v175
	ds_read_b128 v[184:187], v175 offset:1024
	ds_read_b128 v[190:193], v175 offset:2048
	ds_read_b128 v[194:197], v175 offset:3072
	ds_read_b128 v[198:201], v175 offset:4096
	ds_read_b128 v[202:205], v175 offset:5120
	ds_read_b128 v[206:209], v175 offset:6144
	ds_read_b128 v[210:213], v175 offset:7168
	global_load_lds_dwordx4 v156, s[2:3]
	s_add_i32 m0, s50, 0xe000
	s_nop 0
	global_load_lds_dwordx4 v158, s[2:3]
	s_waitcnt lgkmcnt(8)
	s_barrier
	s_waitcnt lgkmcnt(0)
	s_setprio 1
	s_waitcnt lgkmcnt(0)
	v_mfma_f32_16x16x32_bf16 v[126:129], v[130:133], v[180:183], v[126:129]
	v_mfma_f32_16x16x32_bf16 v[122:125], v[138:141], v[180:183], v[122:125]
	v_mfma_f32_16x16x32_bf16 v[118:121], v[130:133], v[190:193], v[118:121]
	v_mfma_f32_16x16x32_bf16 v[110:113], v[138:141], v[190:193], v[110:113]
	v_mfma_f32_16x16x32_bf16 v[102:105], v[130:133], v[198:201], v[102:105]
	v_mfma_f32_16x16x32_bf16 v[94:97], v[138:141], v[198:201], v[94:97]
	v_mfma_f32_16x16x32_bf16 v[86:89], v[130:133], v[206:209], v[86:89]
	v_mfma_f32_16x16x32_bf16 v[78:81], v[138:141], v[206:209], v[78:81]
	v_mfma_f32_16x16x32_bf16 v[126:129], v[134:137], v[184:187], v[126:129]
	v_mfma_f32_16x16x32_bf16 v[122:125], v[142:145], v[184:187], v[122:125]
	v_mfma_f32_16x16x32_bf16 v[118:121], v[134:137], v[194:197], v[118:121]
	v_mfma_f32_16x16x32_bf16 v[110:113], v[142:145], v[194:197], v[110:113]
	v_mfma_f32_16x16x32_bf16 v[102:105], v[134:137], v[202:205], v[102:105]
	v_mfma_f32_16x16x32_bf16 v[94:97], v[142:145], v[202:205], v[94:97]
	v_mfma_f32_16x16x32_bf16 v[86:89], v[134:137], v[210:213], v[86:89]
	v_mfma_f32_16x16x32_bf16 v[78:81], v[142:145], v[210:213], v[78:81]
	s_setprio 0
	s_barrier
	s_add_i32 s74, s66, s49
	s_add_u32 s98, s6, 0x80
	s_addc_u32 s99, s7, 0
	s_mov_b32 m0, s74
	ds_read_b128 v[214:217], v177
	ds_read_b128 v[218:221], v177 offset:1024
	ds_read_b128 v[222:225], v177 offset:2048
	ds_read_b128 v[226:229], v177 offset:3072
	global_load_lds_dwordx4 v148, s[6:7]
	s_add_i32 m0, s74, 0x2000
	s_nop 0
	global_load_lds_dwordx4 v152, s[6:7]
	s_barrier
	s_waitcnt lgkmcnt(0)
	s_setprio 1
	s_waitcnt lgkmcnt(0)
	v_mfma_f32_16x16x32_bf16 v[114:117], v[214:217], v[180:183], v[114:117]
	v_mfma_f32_16x16x32_bf16 v[106:109], v[222:225], v[180:183], v[106:109]
	v_mfma_f32_16x16x32_bf16 v[98:101], v[214:217], v[190:193], v[98:101]
	v_mfma_f32_16x16x32_bf16 v[90:93], v[222:225], v[190:193], v[90:93]
	v_mfma_f32_16x16x32_bf16 v[82:85], v[214:217], v[198:201], v[82:85]
	v_mfma_f32_16x16x32_bf16 v[74:77], v[222:225], v[198:201], v[74:77]
	v_mfma_f32_16x16x32_bf16 v[70:73], v[214:217], v[206:209], v[70:73]
	v_mfma_f32_16x16x32_bf16 v[66:69], v[222:225], v[206:209], v[66:69]
	v_mfma_f32_16x16x32_bf16 v[114:117], v[218:221], v[184:187], v[114:117]
	v_mfma_f32_16x16x32_bf16 v[106:109], v[226:229], v[184:187], v[106:109]
	v_mfma_f32_16x16x32_bf16 v[98:101], v[218:221], v[194:197], v[98:101]
	v_mfma_f32_16x16x32_bf16 v[90:93], v[226:229], v[194:197], v[90:93]
	v_mfma_f32_16x16x32_bf16 v[82:85], v[218:221], v[202:205], v[82:85]
	v_mfma_f32_16x16x32_bf16 v[74:77], v[226:229], v[202:205], v[74:77]
	v_mfma_f32_16x16x32_bf16 v[70:73], v[218:221], v[210:213], v[70:73]
	v_mfma_f32_16x16x32_bf16 v[66:69], v[226:229], v[210:213], v[66:69]
	s_setprio 0
	s_mov_b32 m0, s50
	s_add_u32 s100, s8, 0x80
	s_addc_u32 s101, s9, 0
	s_barrier
	ds_read_b128 v[180:183], v175 offset:16384
	ds_read_b128 v[184:187], v175 offset:17408
	ds_read_b128 v[190:193], v175 offset:18432
	ds_read_b128 v[194:197], v175 offset:19456
	ds_read_b128 v[198:201], v175 offset:20480
	ds_read_b128 v[202:205], v175 offset:21504
	ds_read_b128 v[206:209], v175 offset:22528
	ds_read_b128 v[210:213], v175 offset:23552
	global_load_lds_dwordx4 v146, s[8:9]
	s_mov_b32 m0, s51
	s_nop 0
	global_load_lds_dwordx4 v150, s[8:9]
	s_barrier
	s_waitcnt lgkmcnt(0)
	s_setprio 1
	s_waitcnt lgkmcnt(0)
	v_mfma_f32_16x16x32_bf16 v[62:65], v[130:133], v[180:183], v[62:65]
	v_mfma_f32_16x16x32_bf16 v[58:61], v[138:141], v[180:183], v[58:61]
	v_mfma_f32_16x16x32_bf16 v[54:57], v[130:133], v[190:193], v[54:57]
	v_mfma_f32_16x16x32_bf16 v[46:49], v[138:141], v[190:193], v[46:49]
	v_mfma_f32_16x16x32_bf16 v[38:41], v[130:133], v[198:201], v[38:41]
	v_mfma_f32_16x16x32_bf16 v[30:33], v[138:141], v[198:201], v[30:33]
	v_mfma_f32_16x16x32_bf16 v[22:25], v[130:133], v[206:209], v[22:25]
	v_mfma_f32_16x16x32_bf16 v[14:17], v[138:141], v[206:209], v[14:17]
	v_mfma_f32_16x16x32_bf16 v[62:65], v[134:137], v[184:187], v[62:65]
	v_mfma_f32_16x16x32_bf16 v[58:61], v[142:145], v[184:187], v[58:61]
	v_mfma_f32_16x16x32_bf16 v[54:57], v[134:137], v[194:197], v[54:57]
	v_mfma_f32_16x16x32_bf16 v[46:49], v[142:145], v[194:197], v[46:49]
	v_mfma_f32_16x16x32_bf16 v[38:41], v[134:137], v[202:205], v[38:41]
	v_mfma_f32_16x16x32_bf16 v[30:33], v[142:145], v[202:205], v[30:33]
	v_mfma_f32_16x16x32_bf16 v[22:25], v[134:137], v[210:213], v[22:25]
	v_mfma_f32_16x16x32_bf16 v[14:17], v[142:145], v[210:213], v[14:17]
	s_setprio 0
	s_barrier
	s_add_u32 s74, s6, 0x40000
	s_addc_u32 s75, s7, 0
	s_add_i32 s76, s67, s49
	s_mov_b32 m0, s76
	s_nop 0
	global_load_lds_dwordx4 v148, s[74:75]
	s_add_i32 m0, s76, 0x2000
	s_nop 0
	global_load_lds_dwordx4 v152, s[74:75]
	s_waitcnt vmcnt(6)
	s_barrier
	s_setprio 1
	v_mfma_f32_16x16x32_bf16 v[50:53], v[214:217], v[180:183], v[50:53]
	v_mfma_f32_16x16x32_bf16 v[42:45], v[222:225], v[180:183], v[42:45]
	v_mfma_f32_16x16x32_bf16 v[34:37], v[214:217], v[190:193], v[34:37]
	v_mfma_f32_16x16x32_bf16 v[26:29], v[222:225], v[190:193], v[26:29]
	v_mfma_f32_16x16x32_bf16 v[18:21], v[214:217], v[198:201], v[18:21]
	v_mfma_f32_16x16x32_bf16 v[10:13], v[222:225], v[198:201], v[10:13]
	v_mfma_f32_16x16x32_bf16 v[6:9], v[214:217], v[206:209], v[6:9]
	v_mfma_f32_16x16x32_bf16 v[2:5], v[222:225], v[206:209], v[2:5]
	v_mfma_f32_16x16x32_bf16 v[50:53], v[218:221], v[184:187], v[50:53]
	v_mfma_f32_16x16x32_bf16 v[42:45], v[226:229], v[184:187], v[42:45]
	v_mfma_f32_16x16x32_bf16 v[34:37], v[218:221], v[194:197], v[34:37]
	v_mfma_f32_16x16x32_bf16 v[26:29], v[226:229], v[194:197], v[26:29]
	v_mfma_f32_16x16x32_bf16 v[18:21], v[218:221], v[202:205], v[18:21]
	v_mfma_f32_16x16x32_bf16 v[10:13], v[226:229], v[202:205], v[10:13]
	v_mfma_f32_16x16x32_bf16 v[6:9], v[218:221], v[210:213], v[6:9]
	v_mfma_f32_16x16x32_bf16 v[2:5], v[226:229], v[210:213], v[2:5]
	s_setprio 0
	s_add_i32 s74, 0, 0x18000
	v_add_u32_e32 v142, s74, v171
	s_barrier
	ds_read_b128 v[130:133], v142
	ds_read_b128 v[134:137], v142 offset:1024
	ds_read_b128 v[138:141], v142 offset:2048
	ds_read_b128 v[142:145], v142 offset:3072
	s_add_u32 s8, s8, 0x40000
	s_addc_u32 s9, s9, 0
	s_mov_b32 m0, s52
	ds_read_b128 v[180:183], v175 offset:32768
	ds_read_b128 v[184:187], v175 offset:33792
	ds_read_b128 v[190:193], v175 offset:34816
	ds_read_b128 v[194:197], v175 offset:35840
	ds_read_b128 v[198:201], v175 offset:36864
	ds_read_b128 v[202:205], v175 offset:37888
	ds_read_b128 v[206:209], v175 offset:38912
	ds_read_b128 v[210:213], v175 offset:39936
	global_load_lds_dwordx4 v146, s[8:9]
	s_mov_b32 m0, s53
	s_nop 0
	global_load_lds_dwordx4 v150, s[8:9]
	s_waitcnt lgkmcnt(8)
	s_barrier
	s_waitcnt lgkmcnt(0)
	s_setprio 1
	s_waitcnt lgkmcnt(0)
	v_mfma_f32_16x16x32_bf16 v[126:129], v[130:133], v[180:183], v[126:129]
	v_mfma_f32_16x16x32_bf16 v[122:125], v[138:141], v[180:183], v[122:125]
	v_mfma_f32_16x16x32_bf16 v[118:121], v[130:133], v[190:193], v[118:121]
	v_mfma_f32_16x16x32_bf16 v[110:113], v[138:141], v[190:193], v[110:113]
	v_mfma_f32_16x16x32_bf16 v[102:105], v[130:133], v[198:201], v[102:105]
	v_mfma_f32_16x16x32_bf16 v[94:97], v[138:141], v[198:201], v[94:97]
	v_mfma_f32_16x16x32_bf16 v[86:89], v[130:133], v[206:209], v[86:89]
	v_mfma_f32_16x16x32_bf16 v[78:81], v[138:141], v[206:209], v[78:81]
	v_mfma_f32_16x16x32_bf16 v[126:129], v[134:137], v[184:187], v[126:129]
	v_mfma_f32_16x16x32_bf16 v[122:125], v[142:145], v[184:187], v[122:125]
	v_mfma_f32_16x16x32_bf16 v[118:121], v[134:137], v[194:197], v[118:121]
	v_mfma_f32_16x16x32_bf16 v[110:113], v[142:145], v[194:197], v[110:113]
	v_mfma_f32_16x16x32_bf16 v[102:105], v[134:137], v[202:205], v[102:105]
	v_mfma_f32_16x16x32_bf16 v[94:97], v[142:145], v[202:205], v[94:97]
	v_mfma_f32_16x16x32_bf16 v[86:89], v[134:137], v[210:213], v[86:89]
	v_mfma_f32_16x16x32_bf16 v[78:81], v[142:145], v[210:213], v[78:81]
	s_setprio 0
	s_barrier
	s_add_i32 s8, 0, 0x1c000
	s_add_i32 s9, s74, s49
	v_add_u32_e32 v154, s8, v171
	s_mov_b32 m0, s9
	ds_read_b128 v[214:217], v154
	ds_read_b128 v[218:221], v154 offset:1024
	ds_read_b128 v[222:225], v154 offset:2048
	ds_read_b128 v[226:229], v154 offset:3072
	global_load_lds_dwordx4 v148, s[98:99]
	s_add_i32 m0, s9, 0x2000
	s_nop 0
	global_load_lds_dwordx4 v152, s[98:99]
	s_barrier
	s_waitcnt lgkmcnt(0)
	s_setprio 1
	s_waitcnt lgkmcnt(0)
	v_mfma_f32_16x16x32_bf16 v[114:117], v[214:217], v[180:183], v[114:117]
	v_mfma_f32_16x16x32_bf16 v[106:109], v[222:225], v[180:183], v[106:109]
	v_mfma_f32_16x16x32_bf16 v[98:101], v[214:217], v[190:193], v[98:101]
	v_mfma_f32_16x16x32_bf16 v[90:93], v[222:225], v[190:193], v[90:93]
	v_mfma_f32_16x16x32_bf16 v[82:85], v[214:217], v[198:201], v[82:85]
	v_mfma_f32_16x16x32_bf16 v[74:77], v[222:225], v[198:201], v[74:77]
	v_mfma_f32_16x16x32_bf16 v[70:73], v[214:217], v[206:209], v[70:73]
	v_mfma_f32_16x16x32_bf16 v[66:69], v[222:225], v[206:209], v[66:69]
	v_mfma_f32_16x16x32_bf16 v[114:117], v[218:221], v[184:187], v[114:117]
	v_mfma_f32_16x16x32_bf16 v[106:109], v[226:229], v[184:187], v[106:109]
	v_mfma_f32_16x16x32_bf16 v[98:101], v[218:221], v[194:197], v[98:101]
	v_mfma_f32_16x16x32_bf16 v[90:93], v[226:229], v[194:197], v[90:93]
	v_mfma_f32_16x16x32_bf16 v[82:85], v[218:221], v[202:205], v[82:85]
	v_mfma_f32_16x16x32_bf16 v[74:77], v[226:229], v[202:205], v[74:77]
	v_mfma_f32_16x16x32_bf16 v[70:73], v[218:221], v[210:213], v[70:73]
	v_mfma_f32_16x16x32_bf16 v[66:69], v[226:229], v[210:213], v[66:69]
	s_setprio 0
	s_mov_b32 m0, s56
	s_barrier
	ds_read_b128 v[180:183], v175 offset:49152
	ds_read_b128 v[184:187], v175 offset:50176
	ds_read_b128 v[190:193], v175 offset:51200
	ds_read_b128 v[194:197], v175 offset:52224
	ds_read_b128 v[198:201], v175 offset:53248
	ds_read_b128 v[202:205], v175 offset:54272
	ds_read_b128 v[206:209], v175 offset:55296
	ds_read_b128 v[210:213], v175 offset:56320
	global_load_lds_dwordx4 v146, s[100:101]
	s_mov_b32 m0, s57
	s_nop 0
	global_load_lds_dwordx4 v150, s[100:101]
	s_barrier
	s_waitcnt lgkmcnt(0)
	s_setprio 1
	s_waitcnt lgkmcnt(0)
	v_mfma_f32_16x16x32_bf16 v[62:65], v[130:133], v[180:183], v[62:65]
	v_mfma_f32_16x16x32_bf16 v[58:61], v[138:141], v[180:183], v[58:61]
	v_mfma_f32_16x16x32_bf16 v[54:57], v[130:133], v[190:193], v[54:57]
	v_mfma_f32_16x16x32_bf16 v[46:49], v[138:141], v[190:193], v[46:49]
	v_mfma_f32_16x16x32_bf16 v[38:41], v[130:133], v[198:201], v[38:41]
	v_mfma_f32_16x16x32_bf16 v[30:33], v[138:141], v[198:201], v[30:33]
	v_mfma_f32_16x16x32_bf16 v[22:25], v[130:133], v[206:209], v[22:25]
	v_mfma_f32_16x16x32_bf16 v[14:17], v[138:141], v[206:209], v[14:17]
	v_mfma_f32_16x16x32_bf16 v[62:65], v[134:137], v[184:187], v[62:65]
	v_mfma_f32_16x16x32_bf16 v[58:61], v[142:145], v[184:187], v[58:61]
	v_mfma_f32_16x16x32_bf16 v[54:57], v[134:137], v[194:197], v[54:57]
	v_mfma_f32_16x16x32_bf16 v[46:49], v[142:145], v[194:197], v[46:49]
	v_mfma_f32_16x16x32_bf16 v[38:41], v[134:137], v[202:205], v[38:41]
	v_mfma_f32_16x16x32_bf16 v[30:33], v[142:145], v[202:205], v[30:33]
	v_mfma_f32_16x16x32_bf16 v[22:25], v[134:137], v[210:213], v[22:25]
	v_mfma_f32_16x16x32_bf16 v[14:17], v[142:145], v[210:213], v[14:17]
	s_setprio 0
	s_barrier
	s_add_u32 s6, s6, 0x40080
	s_addc_u32 s7, s7, 0
	s_add_i32 s8, s8, s49
	s_mov_b32 m0, s8
	s_nop 0
	global_load_lds_dwordx4 v148, s[6:7]
	s_add_i32 m0, s8, 0x2000
	s_nop 0
	global_load_lds_dwordx4 v152, s[6:7]
	s_waitcnt vmcnt(6)
	s_barrier
	s_setprio 1
	v_mfma_f32_16x16x32_bf16 v[50:53], v[214:217], v[180:183], v[50:53]
	v_mfma_f32_16x16x32_bf16 v[42:45], v[222:225], v[180:183], v[42:45]
	v_mfma_f32_16x16x32_bf16 v[34:37], v[214:217], v[190:193], v[34:37]
	v_mfma_f32_16x16x32_bf16 v[26:29], v[222:225], v[190:193], v[26:29]
	v_mfma_f32_16x16x32_bf16 v[18:21], v[214:217], v[198:201], v[18:21]
	v_mfma_f32_16x16x32_bf16 v[10:13], v[222:225], v[198:201], v[10:13]
	v_mfma_f32_16x16x32_bf16 v[6:9], v[214:217], v[206:209], v[6:9]
	v_mfma_f32_16x16x32_bf16 v[2:5], v[222:225], v[206:209], v[2:5]
	v_mfma_f32_16x16x32_bf16 v[50:53], v[218:221], v[184:187], v[50:53]
	v_mfma_f32_16x16x32_bf16 v[42:45], v[226:229], v[184:187], v[42:45]
	v_mfma_f32_16x16x32_bf16 v[34:37], v[218:221], v[194:197], v[34:37]
	v_mfma_f32_16x16x32_bf16 v[26:29], v[226:229], v[194:197], v[26:29]
	v_mfma_f32_16x16x32_bf16 v[18:21], v[218:221], v[202:205], v[18:21]
	v_mfma_f32_16x16x32_bf16 v[10:13], v[226:229], v[202:205], v[10:13]
	v_mfma_f32_16x16x32_bf16 v[6:9], v[218:221], v[210:213], v[6:9]
	v_mfma_f32_16x16x32_bf16 v[2:5], v[226:229], v[210:213], v[2:5]
	s_setprio 0
	s_add_i32 s73, s73, 2
	s_add_u32 s2, s2, 0x100
	s_addc_u32 s3, s3, 0
	s_add_u32 s71, s71, 0x100
	s_addc_u32 s72, s72, 0
	s_cmp_gt_u32 s73, 13
	s_barrier
	s_cbranch_scc0 .LBB0_212

.Lpeel_p8:
	ds_read_b128 v[130:133], v181
	ds_read_b128 v[134:137], v181 offset:1024
	ds_read_b128 v[138:141], v181 offset:2048
	ds_read_b128 v[142:145], v181 offset:3072
	s_add_u32 s2, s0, 0xfffc0080
	s_addc_u32 s3, s1, -1
	s_cmp_eq_u32 s74, 12
	s_cselect_b32 s45, s33, s3
	s_cselect_b32 s44, s39, s2
	s_cselect_b32 s3, s37, s73
	s_cselect_b32 s2, s71, s72
	s_add_i32 m0, s52, 0xc000
	ds_read_b128 v[146:149], v183
	ds_read_b128 v[150:153], v183 offset:1024
	ds_read_b128 v[154:157], v183 offset:2048
	ds_read_b128 v[158:161], v183 offset:3072
	ds_read_b128 v[162:165], v183 offset:4096
	ds_read_b128 v[166:169], v183 offset:5120
	ds_read_b128 v[170:173], v183 offset:6144
	ds_read_b128 v[174:177], v183 offset:7168
	global_load_lds_dwordx4 v192, s[0:1]
	s_add_i32 m0, s52, 0xe000
	s_nop 0
	global_load_lds_dwordx4 v194, s[0:1]
	s_waitcnt lgkmcnt(8)
	s_barrier
	s_waitcnt lgkmcnt(0)
	s_setprio 1
	s_waitcnt lgkmcnt(0)
	v_mfma_f32_16x16x32_bf16 v[62:65], v[130:133], v[146:149], 0
	v_mfma_f32_16x16x32_bf16 v[30:33], v[138:141], v[146:149], 0
	v_mfma_f32_16x16x32_bf16 v[54:57], v[130:133], v[154:157], 0
	v_mfma_f32_16x16x32_bf16 v[22:25], v[138:141], v[154:157], 0
	v_mfma_f32_16x16x32_bf16 v[46:49], v[130:133], v[162:165], 0
	v_mfma_f32_16x16x32_bf16 v[14:17], v[138:141], v[162:165], 0
	v_mfma_f32_16x16x32_bf16 v[38:41], v[130:133], v[170:173], 0
	v_mfma_f32_16x16x32_bf16 v[6:9], v[138:141], v[170:173], 0
	v_mfma_f32_16x16x32_bf16 v[62:65], v[134:137], v[150:153], v[62:65]
	v_mfma_f32_16x16x32_bf16 v[30:33], v[142:145], v[150:153], v[30:33]
	v_mfma_f32_16x16x32_bf16 v[54:57], v[134:137], v[158:161], v[54:57]
	v_mfma_f32_16x16x32_bf16 v[22:25], v[142:145], v[158:161], v[22:25]
	v_mfma_f32_16x16x32_bf16 v[46:49], v[134:137], v[166:169], v[46:49]
	v_mfma_f32_16x16x32_bf16 v[14:17], v[142:145], v[166:169], v[14:17]
	v_mfma_f32_16x16x32_bf16 v[38:41], v[134:137], v[174:177], v[38:41]
	v_mfma_f32_16x16x32_bf16 v[6:9], v[142:145], v[174:177], v[6:9]
	s_setprio 0
	s_barrier
	s_add_i32 s75, s66, s51
	s_add_u32 s98, s2, 0x80
	s_addc_u32 s99, s3, 0
	s_mov_b32 m0, s75
	ds_read_b128 v[200:203], v206
	ds_read_b128 v[212:215], v206 offset:1024
	ds_read_b128 v[216:219], v206 offset:2048
	ds_read_b128 v[220:223], v206 offset:3072
	global_load_lds_dwordx4 v186, s[2:3]
	s_add_i32 m0, s75, 0x2000
	s_nop 0
	global_load_lds_dwordx4 v190, s[2:3]
	s_barrier
	s_waitcnt lgkmcnt(0)
	s_setprio 1
	s_waitcnt lgkmcnt(0)
	v_mfma_f32_16x16x32_bf16 v[58:61], v[200:203], v[146:149], 0
	v_mfma_f32_16x16x32_bf16 v[26:29], v[216:219], v[146:149], 0
	v_mfma_f32_16x16x32_bf16 v[50:53], v[200:203], v[154:157], 0
	v_mfma_f32_16x16x32_bf16 v[18:21], v[216:219], v[154:157], 0
	v_mfma_f32_16x16x32_bf16 v[42:45], v[200:203], v[162:165], 0
	v_mfma_f32_16x16x32_bf16 v[10:13], v[216:219], v[162:165], 0
	v_mfma_f32_16x16x32_bf16 v[34:37], v[200:203], v[170:173], 0
	v_mfma_f32_16x16x32_bf16 v[2:5], v[216:219], v[170:173], 0
	v_mfma_f32_16x16x32_bf16 v[58:61], v[212:215], v[150:153], v[58:61]
	v_mfma_f32_16x16x32_bf16 v[26:29], v[220:223], v[150:153], v[26:29]
	v_mfma_f32_16x16x32_bf16 v[50:53], v[212:215], v[158:161], v[50:53]
	v_mfma_f32_16x16x32_bf16 v[18:21], v[220:223], v[158:161], v[18:21]
	v_mfma_f32_16x16x32_bf16 v[42:45], v[212:215], v[166:169], v[42:45]
	v_mfma_f32_16x16x32_bf16 v[10:13], v[220:223], v[166:169], v[10:13]
	v_mfma_f32_16x16x32_bf16 v[34:37], v[212:215], v[174:177], v[34:37]
	v_mfma_f32_16x16x32_bf16 v[2:5], v[220:223], v[174:177], v[2:5]
	s_setprio 0
	s_mov_b32 m0, s52
	s_add_u32 s100, s44, 0x80
	s_addc_u32 s101, s45, 0
	s_barrier
	ds_read_b128 v[146:149], v183 offset:16384
	ds_read_b128 v[150:153], v183 offset:17408
	ds_read_b128 v[154:157], v183 offset:18432
	ds_read_b128 v[158:161], v183 offset:19456
	ds_read_b128 v[162:165], v183 offset:20480
	ds_read_b128 v[166:169], v183 offset:21504
	ds_read_b128 v[170:173], v183 offset:22528
	ds_read_b128 v[174:177], v183 offset:23552
	global_load_lds_dwordx4 v184, s[44:45]
	s_mov_b32 m0, s53
	s_nop 0
	global_load_lds_dwordx4 v188, s[44:45]
	s_barrier
	s_waitcnt lgkmcnt(0)
	s_setprio 1
	s_waitcnt lgkmcnt(0)
	v_mfma_f32_16x16x32_bf16 v[126:129], v[130:133], v[146:149], 0
	v_mfma_f32_16x16x32_bf16 v[102:105], v[138:141], v[146:149], 0
	v_mfma_f32_16x16x32_bf16 v[122:125], v[130:133], v[154:157], 0
	v_mfma_f32_16x16x32_bf16 v[90:93], v[138:141], v[154:157], 0
	v_mfma_f32_16x16x32_bf16 v[118:121], v[130:133], v[162:165], 0
	v_mfma_f32_16x16x32_bf16 v[78:81], v[138:141], v[162:165], 0
	v_mfma_f32_16x16x32_bf16 v[106:109], v[130:133], v[170:173], 0
	v_mfma_f32_16x16x32_bf16 v[70:73], v[138:141], v[170:173], 0
	v_mfma_f32_16x16x32_bf16 v[126:129], v[134:137], v[150:153], v[126:129]
	v_mfma_f32_16x16x32_bf16 v[102:105], v[142:145], v[150:153], v[102:105]
	v_mfma_f32_16x16x32_bf16 v[122:125], v[134:137], v[158:161], v[122:125]
	v_mfma_f32_16x16x32_bf16 v[90:93], v[142:145], v[158:161], v[90:93]
	v_mfma_f32_16x16x32_bf16 v[118:121], v[134:137], v[166:169], v[118:121]
	v_mfma_f32_16x16x32_bf16 v[78:81], v[142:145], v[166:169], v[78:81]
	v_mfma_f32_16x16x32_bf16 v[106:109], v[134:137], v[174:177], v[106:109]
	v_mfma_f32_16x16x32_bf16 v[70:73], v[142:145], v[174:177], v[70:73]
	s_setprio 0
	s_barrier
	s_add_u32 s76, s2, 0x40000
	s_addc_u32 s77, s3, 0
	s_add_i32 s75, s67, s51
	s_mov_b32 m0, s75
	s_nop 0
	global_load_lds_dwordx4 v186, s[76:77]
	s_add_i32 m0, s75, 0x2000
	s_nop 0
	global_load_lds_dwordx4 v190, s[76:77]
	s_waitcnt vmcnt(6)
	s_barrier
	s_setprio 1
	v_mfma_f32_16x16x32_bf16 v[114:117], v[200:203], v[146:149], 0
	v_mfma_f32_16x16x32_bf16 v[86:89], v[216:219], v[146:149], 0
	v_mfma_f32_16x16x32_bf16 v[110:113], v[200:203], v[154:157], 0
	v_mfma_f32_16x16x32_bf16 v[82:85], v[216:219], v[154:157], 0
	v_mfma_f32_16x16x32_bf16 v[98:101], v[200:203], v[162:165], 0
	v_mfma_f32_16x16x32_bf16 v[74:77], v[216:219], v[162:165], 0
	v_mfma_f32_16x16x32_bf16 v[94:97], v[200:203], v[170:173], 0
	v_mfma_f32_16x16x32_bf16 v[66:69], v[216:219], v[170:173], 0
	v_mfma_f32_16x16x32_bf16 v[114:117], v[212:215], v[150:153], v[114:117]
	v_mfma_f32_16x16x32_bf16 v[86:89], v[220:223], v[150:153], v[86:89]
	v_mfma_f32_16x16x32_bf16 v[110:113], v[212:215], v[158:161], v[110:113]
	v_mfma_f32_16x16x32_bf16 v[82:85], v[220:223], v[158:161], v[82:85]
	v_mfma_f32_16x16x32_bf16 v[98:101], v[212:215], v[166:169], v[98:101]
	v_mfma_f32_16x16x32_bf16 v[74:77], v[220:223], v[166:169], v[74:77]
	v_mfma_f32_16x16x32_bf16 v[94:97], v[212:215], v[174:177], v[94:97]
	v_mfma_f32_16x16x32_bf16 v[66:69], v[220:223], v[174:177], v[66:69]
	s_setprio 0
	s_add_i32 s75, 0, 0x18000
	v_add_u32_e32 v142, s75, v1
	s_barrier
	ds_read_b128 v[130:133], v142
	ds_read_b128 v[134:137], v142 offset:1024
	ds_read_b128 v[138:141], v142 offset:2048
	ds_read_b128 v[142:145], v142 offset:3072
	s_add_u32 s44, s44, 0x40000
	s_addc_u32 s45, s45, 0
	s_mov_b32 m0, s54
	ds_read_b128 v[146:149], v183 offset:32768
	ds_read_b128 v[150:153], v183 offset:33792
	ds_read_b128 v[154:157], v183 offset:34816
	ds_read_b128 v[158:161], v183 offset:35840
	ds_read_b128 v[162:165], v183 offset:36864
	ds_read_b128 v[166:169], v183 offset:37888
	ds_read_b128 v[170:173], v183 offset:38912
	ds_read_b128 v[174:177], v183 offset:39936
	global_load_lds_dwordx4 v184, s[44:45]
	s_mov_b32 m0, s55
	s_nop 0
	global_load_lds_dwordx4 v188, s[44:45]
	s_waitcnt lgkmcnt(8)
	s_barrier
	s_waitcnt lgkmcnt(0)
	s_setprio 1
	s_waitcnt lgkmcnt(0)
	v_mfma_f32_16x16x32_bf16 v[62:65], v[130:133], v[146:149], v[62:65]
	v_mfma_f32_16x16x32_bf16 v[30:33], v[138:141], v[146:149], v[30:33]
	v_mfma_f32_16x16x32_bf16 v[54:57], v[130:133], v[154:157], v[54:57]
	v_mfma_f32_16x16x32_bf16 v[22:25], v[138:141], v[154:157], v[22:25]
	v_mfma_f32_16x16x32_bf16 v[46:49], v[130:133], v[162:165], v[46:49]
	v_mfma_f32_16x16x32_bf16 v[14:17], v[138:141], v[162:165], v[14:17]
	v_mfma_f32_16x16x32_bf16 v[38:41], v[130:133], v[170:173], v[38:41]
	v_mfma_f32_16x16x32_bf16 v[6:9], v[138:141], v[170:173], v[6:9]
	v_mfma_f32_16x16x32_bf16 v[62:65], v[134:137], v[150:153], v[62:65]
	v_mfma_f32_16x16x32_bf16 v[30:33], v[142:145], v[150:153], v[30:33]
	v_mfma_f32_16x16x32_bf16 v[54:57], v[134:137], v[158:161], v[54:57]
	v_mfma_f32_16x16x32_bf16 v[22:25], v[142:145], v[158:161], v[22:25]
	v_mfma_f32_16x16x32_bf16 v[46:49], v[134:137], v[166:169], v[46:49]
	v_mfma_f32_16x16x32_bf16 v[14:17], v[142:145], v[166:169], v[14:17]
	v_mfma_f32_16x16x32_bf16 v[38:41], v[134:137], v[174:177], v[38:41]
	v_mfma_f32_16x16x32_bf16 v[6:9], v[142:145], v[174:177], v[6:9]
	s_setprio 0
	s_barrier
	s_add_i32 s44, 0, 0x1c000
	s_add_i32 s45, s75, s51
	v_add_u32_e32 v207, s44, v1
	s_mov_b32 m0, s45
	ds_read_b128 v[200:203], v207
	ds_read_b128 v[212:215], v207 offset:1024
	ds_read_b128 v[216:219], v207 offset:2048
	ds_read_b128 v[220:223], v207 offset:3072
	global_load_lds_dwordx4 v186, s[98:99]
	s_add_i32 m0, s45, 0x2000
	s_nop 0
	global_load_lds_dwordx4 v190, s[98:99]
	s_barrier
	s_waitcnt lgkmcnt(0)
	s_setprio 1
	s_waitcnt lgkmcnt(0)
	v_mfma_f32_16x16x32_bf16 v[58:61], v[200:203], v[146:149], v[58:61]
	v_mfma_f32_16x16x32_bf16 v[26:29], v[216:219], v[146:149], v[26:29]
	v_mfma_f32_16x16x32_bf16 v[50:53], v[200:203], v[154:157], v[50:53]
	v_mfma_f32_16x16x32_bf16 v[18:21], v[216:219], v[154:157], v[18:21]
	v_mfma_f32_16x16x32_bf16 v[42:45], v[200:203], v[162:165], v[42:45]
	v_mfma_f32_16x16x32_bf16 v[10:13], v[216:219], v[162:165], v[10:13]
	v_mfma_f32_16x16x32_bf16 v[34:37], v[200:203], v[170:173], v[34:37]
	v_mfma_f32_16x16x32_bf16 v[2:5], v[216:219], v[170:173], v[2:5]
	v_mfma_f32_16x16x32_bf16 v[58:61], v[212:215], v[150:153], v[58:61]
	v_mfma_f32_16x16x32_bf16 v[26:29], v[220:223], v[150:153], v[26:29]
	v_mfma_f32_16x16x32_bf16 v[50:53], v[212:215], v[158:161], v[50:53]
	v_mfma_f32_16x16x32_bf16 v[18:21], v[220:223], v[158:161], v[18:21]
	v_mfma_f32_16x16x32_bf16 v[42:45], v[212:215], v[166:169], v[42:45]
	v_mfma_f32_16x16x32_bf16 v[10:13], v[220:223], v[166:169], v[10:13]
	v_mfma_f32_16x16x32_bf16 v[34:37], v[212:215], v[174:177], v[34:37]
	v_mfma_f32_16x16x32_bf16 v[2:5], v[220:223], v[174:177], v[2:5]
	s_setprio 0
	s_mov_b32 m0, s59
	s_barrier
	ds_read_b128 v[146:149], v183 offset:49152
	ds_read_b128 v[150:153], v183 offset:50176
	ds_read_b128 v[154:157], v183 offset:51200
	ds_read_b128 v[158:161], v183 offset:52224
	ds_read_b128 v[162:165], v183 offset:53248
	ds_read_b128 v[166:169], v183 offset:54272
	ds_read_b128 v[170:173], v183 offset:55296
	ds_read_b128 v[174:177], v183 offset:56320
	global_load_lds_dwordx4 v184, s[100:101]
	s_mov_b32 m0, s60
	s_nop 0
	global_load_lds_dwordx4 v188, s[100:101]
	s_barrier
	s_waitcnt lgkmcnt(0)
	s_setprio 1
	s_waitcnt lgkmcnt(0)
	v_mfma_f32_16x16x32_bf16 v[126:129], v[130:133], v[146:149], v[126:129]
	v_mfma_f32_16x16x32_bf16 v[102:105], v[138:141], v[146:149], v[102:105]
	v_mfma_f32_16x16x32_bf16 v[122:125], v[130:133], v[154:157], v[122:125]
	v_mfma_f32_16x16x32_bf16 v[90:93], v[138:141], v[154:157], v[90:93]
	v_mfma_f32_16x16x32_bf16 v[118:121], v[130:133], v[162:165], v[118:121]
	v_mfma_f32_16x16x32_bf16 v[78:81], v[138:141], v[162:165], v[78:81]
	v_mfma_f32_16x16x32_bf16 v[106:109], v[130:133], v[170:173], v[106:109]
	v_mfma_f32_16x16x32_bf16 v[70:73], v[138:141], v[170:173], v[70:73]
	v_mfma_f32_16x16x32_bf16 v[126:129], v[134:137], v[150:153], v[126:129]
	v_mfma_f32_16x16x32_bf16 v[102:105], v[142:145], v[150:153], v[102:105]
	v_mfma_f32_16x16x32_bf16 v[122:125], v[134:137], v[158:161], v[122:125]
	v_mfma_f32_16x16x32_bf16 v[90:93], v[142:145], v[158:161], v[90:93]
	v_mfma_f32_16x16x32_bf16 v[118:121], v[134:137], v[166:169], v[118:121]
	v_mfma_f32_16x16x32_bf16 v[78:81], v[142:145], v[166:169], v[78:81]
	v_mfma_f32_16x16x32_bf16 v[106:109], v[134:137], v[174:177], v[106:109]
	v_mfma_f32_16x16x32_bf16 v[70:73], v[142:145], v[174:177], v[70:73]
	s_setprio 0
	s_barrier
	s_add_u32 s2, s2, 0x40080
	s_addc_u32 s3, s3, 0
	s_add_i32 s44, s44, s51
	s_mov_b32 m0, s44
	s_nop 0
	global_load_lds_dwordx4 v186, s[2:3]
	s_add_i32 m0, s44, 0x2000
	s_nop 0
	global_load_lds_dwordx4 v190, s[2:3]
	s_waitcnt vmcnt(6)
	s_barrier
	s_setprio 1
	v_mfma_f32_16x16x32_bf16 v[114:117], v[200:203], v[146:149], v[114:117]
	v_mfma_f32_16x16x32_bf16 v[86:89], v[216:219], v[146:149], v[86:89]
	v_mfma_f32_16x16x32_bf16 v[110:113], v[200:203], v[154:157], v[110:113]
	v_mfma_f32_16x16x32_bf16 v[82:85], v[216:219], v[154:157], v[82:85]
	v_mfma_f32_16x16x32_bf16 v[98:101], v[200:203], v[162:165], v[98:101]
	v_mfma_f32_16x16x32_bf16 v[74:77], v[216:219], v[162:165], v[74:77]
	v_mfma_f32_16x16x32_bf16 v[94:97], v[200:203], v[170:173], v[94:97]
	v_mfma_f32_16x16x32_bf16 v[66:69], v[216:219], v[170:173], v[66:69]
	v_mfma_f32_16x16x32_bf16 v[114:117], v[212:215], v[150:153], v[114:117]
	v_mfma_f32_16x16x32_bf16 v[86:89], v[220:223], v[150:153], v[86:89]
	v_mfma_f32_16x16x32_bf16 v[110:113], v[212:215], v[158:161], v[110:113]
	v_mfma_f32_16x16x32_bf16 v[82:85], v[220:223], v[158:161], v[82:85]
	v_mfma_f32_16x16x32_bf16 v[98:101], v[212:215], v[166:169], v[98:101]
	v_mfma_f32_16x16x32_bf16 v[74:77], v[220:223], v[166:169], v[74:77]
	v_mfma_f32_16x16x32_bf16 v[94:97], v[212:215], v[174:177], v[94:97]
	v_mfma_f32_16x16x32_bf16 v[66:69], v[220:223], v[174:177], v[66:69]
	s_setprio 0
	s_add_i32 s74, s74, 2
	s_add_u32 s0, s0, 0x100
	s_addc_u32 s1, s1, 0
	s_add_u32 s72, s72, 0x100
	s_addc_u32 s73, s73, 0
	s_cmp_gt_u32 s74, 13
	s_barrier
	s_cbranch_scc1 .Lpeel_p8_exit
.LBB0_1090:
	ds_read_b128 v[130:133], v181
	ds_read_b128 v[134:137], v181 offset:1024
	ds_read_b128 v[138:141], v181 offset:2048
	ds_read_b128 v[142:145], v181 offset:3072
	s_add_u32 s2, s0, 0xfffc0080
	s_addc_u32 s3, s1, -1
	s_cmp_eq_u32 s74, 12
	s_cselect_b32 s45, s33, s3
	s_cselect_b32 s44, s39, s2
	s_cselect_b32 s3, s37, s73
	s_cselect_b32 s2, s71, s72
	s_add_i32 m0, s52, 0xc000
	ds_read_b128 v[146:149], v183
	ds_read_b128 v[150:153], v183 offset:1024
	ds_read_b128 v[154:157], v183 offset:2048
	ds_read_b128 v[158:161], v183 offset:3072
	ds_read_b128 v[162:165], v183 offset:4096
	ds_read_b128 v[166:169], v183 offset:5120
	ds_read_b128 v[170:173], v183 offset:6144
	ds_read_b128 v[174:177], v183 offset:7168
	global_load_lds_dwordx4 v192, s[0:1]
	s_add_i32 m0, s52, 0xe000
	s_nop 0
	global_load_lds_dwordx4 v194, s[0:1]
	s_waitcnt lgkmcnt(8)
	s_barrier
	s_waitcnt lgkmcnt(0)
	s_setprio 1
	s_waitcnt lgkmcnt(0)
	v_mfma_f32_16x16x32_bf16 v[62:65], v[130:133], v[146:149], v[62:65]
	v_mfma_f32_16x16x32_bf16 v[30:33], v[138:141], v[146:149], v[30:33]
	v_mfma_f32_16x16x32_bf16 v[54:57], v[130:133], v[154:157], v[54:57]
	v_mfma_f32_16x16x32_bf16 v[22:25], v[138:141], v[154:157], v[22:25]
	v_mfma_f32_16x16x32_bf16 v[46:49], v[130:133], v[162:165], v[46:49]
	v_mfma_f32_16x16x32_bf16 v[14:17], v[138:141], v[162:165], v[14:17]
	v_mfma_f32_16x16x32_bf16 v[38:41], v[130:133], v[170:173], v[38:41]
	v_mfma_f32_16x16x32_bf16 v[6:9], v[138:141], v[170:173], v[6:9]
	v_mfma_f32_16x16x32_bf16 v[62:65], v[134:137], v[150:153], v[62:65]
	v_mfma_f32_16x16x32_bf16 v[30:33], v[142:145], v[150:153], v[30:33]
	v_mfma_f32_16x16x32_bf16 v[54:57], v[134:137], v[158:161], v[54:57]
	v_mfma_f32_16x16x32_bf16 v[22:25], v[142:145], v[158:161], v[22:25]
	v_mfma_f32_16x16x32_bf16 v[46:49], v[134:137], v[166:169], v[46:49]
	v_mfma_f32_16x16x32_bf16 v[14:17], v[142:145], v[166:169], v[14:17]
	v_mfma_f32_16x16x32_bf16 v[38:41], v[134:137], v[174:177], v[38:41]
	v_mfma_f32_16x16x32_bf16 v[6:9], v[142:145], v[174:177], v[6:9]
	s_setprio 0
	s_barrier
	s_add_i32 s75, s66, s51
	s_add_u32 s98, s2, 0x80
	s_addc_u32 s99, s3, 0
	s_mov_b32 m0, s75
	ds_read_b128 v[200:203], v206
	ds_read_b128 v[212:215], v206 offset:1024
	ds_read_b128 v[216:219], v206 offset:2048
	ds_read_b128 v[220:223], v206 offset:3072
	global_load_lds_dwordx4 v186, s[2:3]
	s_add_i32 m0, s75, 0x2000
	s_nop 0
	global_load_lds_dwordx4 v190, s[2:3]
	s_barrier
	s_waitcnt lgkmcnt(0)
	s_setprio 1
	s_waitcnt lgkmcnt(0)
	v_mfma_f32_16x16x32_bf16 v[58:61], v[200:203], v[146:149], v[58:61]
	v_mfma_f32_16x16x32_bf16 v[26:29], v[216:219], v[146:149], v[26:29]
	v_mfma_f32_16x16x32_bf16 v[50:53], v[200:203], v[154:157], v[50:53]
	v_mfma_f32_16x16x32_bf16 v[18:21], v[216:219], v[154:157], v[18:21]
	v_mfma_f32_16x16x32_bf16 v[42:45], v[200:203], v[162:165], v[42:45]
	v_mfma_f32_16x16x32_bf16 v[10:13], v[216:219], v[162:165], v[10:13]
	v_mfma_f32_16x16x32_bf16 v[34:37], v[200:203], v[170:173], v[34:37]
	v_mfma_f32_16x16x32_bf16 v[2:5], v[216:219], v[170:173], v[2:5]
	v_mfma_f32_16x16x32_bf16 v[58:61], v[212:215], v[150:153], v[58:61]
	v_mfma_f32_16x16x32_bf16 v[26:29], v[220:223], v[150:153], v[26:29]
	v_mfma_f32_16x16x32_bf16 v[50:53], v[212:215], v[158:161], v[50:53]
	v_mfma_f32_16x16x32_bf16 v[18:21], v[220:223], v[158:161], v[18:21]
	v_mfma_f32_16x16x32_bf16 v[42:45], v[212:215], v[166:169], v[42:45]
	v_mfma_f32_16x16x32_bf16 v[10:13], v[220:223], v[166:169], v[10:13]
	v_mfma_f32_16x16x32_bf16 v[34:37], v[212:215], v[174:177], v[34:37]
	v_mfma_f32_16x16x32_bf16 v[2:5], v[220:223], v[174:177], v[2:5]
	s_setprio 0
	s_mov_b32 m0, s52
	s_add_u32 s100, s44, 0x80
	s_addc_u32 s101, s45, 0
	s_barrier
	ds_read_b128 v[146:149], v183 offset:16384
	ds_read_b128 v[150:153], v183 offset:17408
	ds_read_b128 v[154:157], v183 offset:18432
	ds_read_b128 v[158:161], v183 offset:19456
	ds_read_b128 v[162:165], v183 offset:20480
	ds_read_b128 v[166:169], v183 offset:21504
	ds_read_b128 v[170:173], v183 offset:22528
	ds_read_b128 v[174:177], v183 offset:23552
	global_load_lds_dwordx4 v184, s[44:45]
	s_mov_b32 m0, s53
	s_nop 0
	global_load_lds_dwordx4 v188, s[44:45]
	s_barrier
	s_waitcnt lgkmcnt(0)
	s_setprio 1
	s_waitcnt lgkmcnt(0)
	v_mfma_f32_16x16x32_bf16 v[126:129], v[130:133], v[146:149], v[126:129]
	v_mfma_f32_16x16x32_bf16 v[102:105], v[138:141], v[146:149], v[102:105]
	v_mfma_f32_16x16x32_bf16 v[122:125], v[130:133], v[154:157], v[122:125]
	v_mfma_f32_16x16x32_bf16 v[90:93], v[138:141], v[154:157], v[90:93]
	v_mfma_f32_16x16x32_bf16 v[118:121], v[130:133], v[162:165], v[118:121]
	v_mfma_f32_16x16x32_bf16 v[78:81], v[138:141], v[162:165], v[78:81]
	v_mfma_f32_16x16x32_bf16 v[106:109], v[130:133], v[170:173], v[106:109]
	v_mfma_f32_16x16x32_bf16 v[70:73], v[138:141], v[170:173], v[70:73]
	v_mfma_f32_16x16x32_bf16 v[126:129], v[134:137], v[150:153], v[126:129]
	v_mfma_f32_16x16x32_bf16 v[102:105], v[142:145], v[150:153], v[102:105]
	v_mfma_f32_16x16x32_bf16 v[122:125], v[134:137], v[158:161], v[122:125]
	v_mfma_f32_16x16x32_bf16 v[90:93], v[142:145], v[158:161], v[90:93]
	v_mfma_f32_16x16x32_bf16 v[118:121], v[134:137], v[166:169], v[118:121]
	v_mfma_f32_16x16x32_bf16 v[78:81], v[142:145], v[166:169], v[78:81]
	v_mfma_f32_16x16x32_bf16 v[106:109], v[134:137], v[174:177], v[106:109]
	v_mfma_f32_16x16x32_bf16 v[70:73], v[142:145], v[174:177], v[70:73]
	s_setprio 0
	s_barrier
	s_add_u32 s76, s2, 0x40000
	s_addc_u32 s77, s3, 0
	s_add_i32 s75, s67, s51
	s_mov_b32 m0, s75
	s_nop 0
	global_load_lds_dwordx4 v186, s[76:77]
	s_add_i32 m0, s75, 0x2000
	s_nop 0
	global_load_lds_dwordx4 v190, s[76:77]
	s_waitcnt vmcnt(6)
	s_barrier
	s_setprio 1
	v_mfma_f32_16x16x32_bf16 v[114:117], v[200:203], v[146:149], v[114:117]
	v_mfma_f32_16x16x32_bf16 v[86:89], v[216:219], v[146:149], v[86:89]
	v_mfma_f32_16x16x32_bf16 v[110:113], v[200:203], v[154:157], v[110:113]
	v_mfma_f32_16x16x32_bf16 v[82:85], v[216:219], v[154:157], v[82:85]
	v_mfma_f32_16x16x32_bf16 v[98:101], v[200:203], v[162:165], v[98:101]
	v_mfma_f32_16x16x32_bf16 v[74:77], v[216:219], v[162:165], v[74:77]
	v_mfma_f32_16x16x32_bf16 v[94:97], v[200:203], v[170:173], v[94:97]
	v_mfma_f32_16x16x32_bf16 v[66:69], v[216:219], v[170:173], v[66:69]
	v_mfma_f32_16x16x32_bf16 v[114:117], v[212:215], v[150:153], v[114:117]
	v_mfma_f32_16x16x32_bf16 v[86:89], v[220:223], v[150:153], v[86:89]
	v_mfma_f32_16x16x32_bf16 v[110:113], v[212:215], v[158:161], v[110:113]
	v_mfma_f32_16x16x32_bf16 v[82:85], v[220:223], v[158:161], v[82:85]
	v_mfma_f32_16x16x32_bf16 v[98:101], v[212:215], v[166:169], v[98:101]
	v_mfma_f32_16x16x32_bf16 v[74:77], v[220:223], v[166:169], v[74:77]
	v_mfma_f32_16x16x32_bf16 v[94:97], v[212:215], v[174:177], v[94:97]
	v_mfma_f32_16x16x32_bf16 v[66:69], v[220:223], v[174:177], v[66:69]
	s_setprio 0
	s_add_i32 s75, 0, 0x18000
	v_add_u32_e32 v142, s75, v1
	s_barrier
	ds_read_b128 v[130:133], v142
	ds_read_b128 v[134:137], v142 offset:1024
	ds_read_b128 v[138:141], v142 offset:2048
	ds_read_b128 v[142:145], v142 offset:3072
	s_add_u32 s44, s44, 0x40000
	s_addc_u32 s45, s45, 0
	s_mov_b32 m0, s54
	ds_read_b128 v[146:149], v183 offset:32768
	ds_read_b128 v[150:153], v183 offset:33792
	ds_read_b128 v[154:157], v183 offset:34816
	ds_read_b128 v[158:161], v183 offset:35840
	ds_read_b128 v[162:165], v183 offset:36864
	ds_read_b128 v[166:169], v183 offset:37888
	ds_read_b128 v[170:173], v183 offset:38912
	ds_read_b128 v[174:177], v183 offset:39936
	global_load_lds_dwordx4 v184, s[44:45]
	s_mov_b32 m0, s55
	s_nop 0
	global_load_lds_dwordx4 v188, s[44:45]
	s_waitcnt lgkmcnt(8)
	s_barrier
	s_waitcnt lgkmcnt(0)
	s_setprio 1
	s_waitcnt lgkmcnt(0)
	v_mfma_f32_16x16x32_bf16 v[62:65], v[130:133], v[146:149], v[62:65]
	v_mfma_f32_16x16x32_bf16 v[30:33], v[138:141], v[146:149], v[30:33]
	v_mfma_f32_16x16x32_bf16 v[54:57], v[130:133], v[154:157], v[54:57]
	v_mfma_f32_16x16x32_bf16 v[22:25], v[138:141], v[154:157], v[22:25]
	v_mfma_f32_16x16x32_bf16 v[46:49], v[130:133], v[162:165], v[46:49]
	v_mfma_f32_16x16x32_bf16 v[14:17], v[138:141], v[162:165], v[14:17]
	v_mfma_f32_16x16x32_bf16 v[38:41], v[130:133], v[170:173], v[38:41]
	v_mfma_f32_16x16x32_bf16 v[6:9], v[138:141], v[170:173], v[6:9]
	v_mfma_f32_16x16x32_bf16 v[62:65], v[134:137], v[150:153], v[62:65]
	v_mfma_f32_16x16x32_bf16 v[30:33], v[142:145], v[150:153], v[30:33]
	v_mfma_f32_16x16x32_bf16 v[54:57], v[134:137], v[158:161], v[54:57]
	v_mfma_f32_16x16x32_bf16 v[22:25], v[142:145], v[158:161], v[22:25]
	v_mfma_f32_16x16x32_bf16 v[46:49], v[134:137], v[166:169], v[46:49]
	v_mfma_f32_16x16x32_bf16 v[14:17], v[142:145], v[166:169], v[14:17]
	v_mfma_f32_16x16x32_bf16 v[38:41], v[134:137], v[174:177], v[38:41]
	v_mfma_f32_16x16x32_bf16 v[6:9], v[142:145], v[174:177], v[6:9]
	s_setprio 0
	s_barrier
	s_add_i32 s44, 0, 0x1c000
	s_add_i32 s45, s75, s51
	v_add_u32_e32 v207, s44, v1
	s_mov_b32 m0, s45
	ds_read_b128 v[200:203], v207
	ds_read_b128 v[212:215], v207 offset:1024
	ds_read_b128 v[216:219], v207 offset:2048
	ds_read_b128 v[220:223], v207 offset:3072
	global_load_lds_dwordx4 v186, s[98:99]
	s_add_i32 m0, s45, 0x2000
	s_nop 0
	global_load_lds_dwordx4 v190, s[98:99]
	s_barrier
	s_waitcnt lgkmcnt(0)
	s_setprio 1
	s_waitcnt lgkmcnt(0)
	v_mfma_f32_16x16x32_bf16 v[58:61], v[200:203], v[146:149], v[58:61]
	v_mfma_f32_16x16x32_bf16 v[26:29], v[216:219], v[146:149], v[26:29]
	v_mfma_f32_16x16x32_bf16 v[50:53], v[200:203], v[154:157], v[50:53]
	v_mfma_f32_16x16x32_bf16 v[18:21], v[216:219], v[154:157], v[18:21]
	v_mfma_f32_16x16x32_bf16 v[42:45], v[200:203], v[162:165], v[42:45]
	v_mfma_f32_16x16x32_bf16 v[10:13], v[216:219], v[162:165], v[10:13]
	v_mfma_f32_16x16x32_bf16 v[34:37], v[200:203], v[170:173], v[34:37]
	v_mfma_f32_16x16x32_bf16 v[2:5], v[216:219], v[170:173], v[2:5]
	v_mfma_f32_16x16x32_bf16 v[58:61], v[212:215], v[150:153], v[58:61]
	v_mfma_f32_16x16x32_bf16 v[26:29], v[220:223], v[150:153], v[26:29]
	v_mfma_f32_16x16x32_bf16 v[50:53], v[212:215], v[158:161], v[50:53]
	v_mfma_f32_16x16x32_bf16 v[18:21], v[220:223], v[158:161], v[18:21]
	v_mfma_f32_16x16x32_bf16 v[42:45], v[212:215], v[166:169], v[42:45]
	v_mfma_f32_16x16x32_bf16 v[10:13], v[220:223], v[166:169], v[10:13]
	v_mfma_f32_16x16x32_bf16 v[34:37], v[212:215], v[174:177], v[34:37]
	v_mfma_f32_16x16x32_bf16 v[2:5], v[220:223], v[174:177], v[2:5]
	s_setprio 0
	s_mov_b32 m0, s59
	s_barrier
	ds_read_b128 v[146:149], v183 offset:49152
	ds_read_b128 v[150:153], v183 offset:50176
	ds_read_b128 v[154:157], v183 offset:51200
	ds_read_b128 v[158:161], v183 offset:52224
	ds_read_b128 v[162:165], v183 offset:53248
	ds_read_b128 v[166:169], v183 offset:54272
	ds_read_b128 v[170:173], v183 offset:55296
	ds_read_b128 v[174:177], v183 offset:56320
	global_load_lds_dwordx4 v184, s[100:101]
	s_mov_b32 m0, s60
	s_nop 0
	global_load_lds_dwordx4 v188, s[100:101]
	s_barrier
	s_waitcnt lgkmcnt(0)
	s_setprio 1
	s_waitcnt lgkmcnt(0)
	v_mfma_f32_16x16x32_bf16 v[126:129], v[130:133], v[146:149], v[126:129]
	v_mfma_f32_16x16x32_bf16 v[102:105], v[138:141], v[146:149], v[102:105]
	v_mfma_f32_16x16x32_bf16 v[122:125], v[130:133], v[154:157], v[122:125]
	v_mfma_f32_16x16x32_bf16 v[90:93], v[138:141], v[154:157], v[90:93]
	v_mfma_f32_16x16x32_bf16 v[118:121], v[130:133], v[162:165], v[118:121]
	v_mfma_f32_16x16x32_bf16 v[78:81], v[138:141], v[162:165], v[78:81]
	v_mfma_f32_16x16x32_bf16 v[106:109], v[130:133], v[170:173], v[106:109]
	v_mfma_f32_16x16x32_bf16 v[70:73], v[138:141], v[170:173], v[70:73]
	v_mfma_f32_16x16x32_bf16 v[126:129], v[134:137], v[150:153], v[126:129]
	v_mfma_f32_16x16x32_bf16 v[102:105], v[142:145], v[150:153], v[102:105]
	v_mfma_f32_16x16x32_bf16 v[122:125], v[134:137], v[158:161], v[122:125]
	v_mfma_f32_16x16x32_bf16 v[90:93], v[142:145], v[158:161], v[90:93]
	v_mfma_f32_16x16x32_bf16 v[118:121], v[134:137], v[166:169], v[118:121]
	v_mfma_f32_16x16x32_bf16 v[78:81], v[142:145], v[166:169], v[78:81]
	v_mfma_f32_16x16x32_bf16 v[106:109], v[134:137], v[174:177], v[106:109]
	v_mfma_f32_16x16x32_bf16 v[70:73], v[142:145], v[174:177], v[70:73]
	s_setprio 0
	s_barrier
	s_add_u32 s2, s2, 0x40080
	s_addc_u32 s3, s3, 0
	s_add_i32 s44, s44, s51
	s_mov_b32 m0, s44
	s_nop 0
	global_load_lds_dwordx4 v186, s[2:3]
	s_add_i32 m0, s44, 0x2000
	s_nop 0
	global_load_lds_dwordx4 v190, s[2:3]
	s_waitcnt vmcnt(6)
	s_barrier
	s_setprio 1
	v_mfma_f32_16x16x32_bf16 v[114:117], v[200:203], v[146:149], v[114:117]
	v_mfma_f32_16x16x32_bf16 v[86:89], v[216:219], v[146:149], v[86:89]
	v_mfma_f32_16x16x32_bf16 v[110:113], v[200:203], v[154:157], v[110:113]
	v_mfma_f32_16x16x32_bf16 v[82:85], v[216:219], v[154:157], v[82:85]
	v_mfma_f32_16x16x32_bf16 v[98:101], v[200:203], v[162:165], v[98:101]
	v_mfma_f32_16x16x32_bf16 v[74:77], v[216:219], v[162:165], v[74:77]
	v_mfma_f32_16x16x32_bf16 v[94:97], v[200:203], v[170:173], v[94:97]
	v_mfma_f32_16x16x32_bf16 v[66:69], v[216:219], v[170:173], v[66:69]
	v_mfma_f32_16x16x32_bf16 v[114:117], v[212:215], v[150:153], v[114:117]
	v_mfma_f32_16x16x32_bf16 v[86:89], v[220:223], v[150:153], v[86:89]
	v_mfma_f32_16x16x32_bf16 v[110:113], v[212:215], v[158:161], v[110:113]
	v_mfma_f32_16x16x32_bf16 v[82:85], v[220:223], v[158:161], v[82:85]
	v_mfma_f32_16x16x32_bf16 v[98:101], v[212:215], v[166:169], v[98:101]
	v_mfma_f32_16x16x32_bf16 v[74:77], v[220:223], v[166:169], v[74:77]
	v_mfma_f32_16x16x32_bf16 v[94:97], v[212:215], v[174:177], v[94:97]
	v_mfma_f32_16x16x32_bf16 v[66:69], v[220:223], v[174:177], v[66:69]
	s_setprio 0
	s_add_i32 s74, s74, 2
	s_add_u32 s0, s0, 0x100
	s_addc_u32 s1, s1, 0
	s_add_u32 s72, s72, 0x100
	s_addc_u32 s73, s73, 0
	s_cmp_gt_u32 s74, 13
	s_barrier
	s_cbranch_scc0 .LBB0_1090

.Lpeel_p10:
	ds_read_b128 v[152:155], v149
	ds_read_b128 v[156:159], v149 offset:1024
	ds_read_b128 v[160:163], v149 offset:2048
	ds_read_b128 v[164:167], v149 offset:3072
	s_add_u32 s18, s16, 0xfff50080
	s_addc_u32 s19, s17, -1
	s_cmp_eq_u32 s54, 40
	s_cselect_b32 s21, s3, s19
	s_cselect_b32 s20, s2, s18
	s_cselect_b32 s19, s5, s53
	s_cselect_b32 s18, s4, s52
	s_add_i32 m0, s30, 0xc000
	ds_read_b128 v[168:171], v150
	ds_read_b128 v[172:175], v150 offset:1024
	ds_read_b128 v[180:183], v150 offset:2048
	ds_read_b128 v[184:187], v150 offset:3072
	ds_read_b128 v[188:191], v150 offset:4096
	ds_read_b128 v[192:195], v150 offset:5120
	ds_read_b128 v[196:199], v150 offset:6144
	ds_read_b128 v[200:203], v150 offset:7168
	global_load_lds_dwordx4 v138, s[16:17]
	s_add_i32 m0, s30, 0xe000
	s_nop 0
	global_load_lds_dwordx4 v140, s[16:17]
	s_waitcnt lgkmcnt(8)
	s_barrier
	s_waitcnt lgkmcnt(0)
	s_setprio 1
	s_waitcnt lgkmcnt(0)
	v_mfma_f32_16x16x32_bf16 v[126:129], v[152:155], v[168:171], 0
	v_mfma_f32_16x16x32_bf16 v[122:125], v[160:163], v[168:171], 0
	v_mfma_f32_16x16x32_bf16 v[114:117], v[152:155], v[180:183], 0
	v_mfma_f32_16x16x32_bf16 v[106:109], v[160:163], v[180:183], 0
	v_mfma_f32_16x16x32_bf16 v[98:101], v[152:155], v[188:191], 0
	v_mfma_f32_16x16x32_bf16 v[90:93], v[160:163], v[188:191], 0
	v_mfma_f32_16x16x32_bf16 v[82:85], v[152:155], v[196:199], 0
	v_mfma_f32_16x16x32_bf16 v[74:77], v[160:163], v[196:199], 0
	v_mfma_f32_16x16x32_bf16 v[126:129], v[156:159], v[172:175], v[126:129]
	v_mfma_f32_16x16x32_bf16 v[122:125], v[164:167], v[172:175], v[122:125]
	v_mfma_f32_16x16x32_bf16 v[114:117], v[156:159], v[184:187], v[114:117]
	v_mfma_f32_16x16x32_bf16 v[106:109], v[164:167], v[184:187], v[106:109]
	v_mfma_f32_16x16x32_bf16 v[98:101], v[156:159], v[192:195], v[98:101]
	v_mfma_f32_16x16x32_bf16 v[90:93], v[164:167], v[192:195], v[90:93]
	v_mfma_f32_16x16x32_bf16 v[82:85], v[156:159], v[200:203], v[82:85]
	v_mfma_f32_16x16x32_bf16 v[74:77], v[164:167], v[200:203], v[74:77]
	s_setprio 0
	s_barrier
	s_add_i32 s55, s41, s27
	s_add_u32 s98, s18, 0x80
	s_addc_u32 s99, s19, 0
	s_mov_b32 m0, s55
	ds_read_b128 v[206:209], v151
	ds_read_b128 v[212:215], v151 offset:1024
	ds_read_b128 v[216:219], v151 offset:2048
	ds_read_b128 v[220:223], v151 offset:3072
	global_load_lds_dwordx4 v134, s[18:19]
	s_add_i32 m0, s55, 0x2000
	s_nop 0
	global_load_lds_dwordx4 v136, s[18:19]
	s_barrier
	s_waitcnt lgkmcnt(0)
	s_setprio 1
	s_waitcnt lgkmcnt(0)
	v_mfma_f32_16x16x32_bf16 v[118:121], v[206:209], v[168:171], 0
	v_mfma_f32_16x16x32_bf16 v[110:113], v[216:219], v[168:171], 0
	v_mfma_f32_16x16x32_bf16 v[102:105], v[206:209], v[180:183], 0
	v_mfma_f32_16x16x32_bf16 v[94:97], v[216:219], v[180:183], 0
	v_mfma_f32_16x16x32_bf16 v[86:89], v[206:209], v[188:191], 0
	v_mfma_f32_16x16x32_bf16 v[78:81], v[216:219], v[188:191], 0
	v_mfma_f32_16x16x32_bf16 v[70:73], v[206:209], v[196:199], 0
	v_mfma_f32_16x16x32_bf16 v[66:69], v[216:219], v[196:199], 0
	v_mfma_f32_16x16x32_bf16 v[118:121], v[212:215], v[172:175], v[118:121]
	v_mfma_f32_16x16x32_bf16 v[110:113], v[220:223], v[172:175], v[110:113]
	v_mfma_f32_16x16x32_bf16 v[102:105], v[212:215], v[184:187], v[102:105]
	v_mfma_f32_16x16x32_bf16 v[94:97], v[220:223], v[184:187], v[94:97]
	v_mfma_f32_16x16x32_bf16 v[86:89], v[212:215], v[192:195], v[86:89]
	v_mfma_f32_16x16x32_bf16 v[78:81], v[220:223], v[192:195], v[78:81]
	v_mfma_f32_16x16x32_bf16 v[70:73], v[212:215], v[200:203], v[70:73]
	v_mfma_f32_16x16x32_bf16 v[66:69], v[220:223], v[200:203], v[66:69]
	s_setprio 0
	s_mov_b32 m0, s30
	s_add_u32 s100, s20, 0x80
	s_addc_u32 s101, s21, 0
	s_barrier
	ds_read_b128 v[168:171], v150 offset:16384
	ds_read_b128 v[172:175], v150 offset:17408
	ds_read_b128 v[180:183], v150 offset:18432
	ds_read_b128 v[184:187], v150 offset:19456
	ds_read_b128 v[188:191], v150 offset:20480
	ds_read_b128 v[192:195], v150 offset:21504
	ds_read_b128 v[196:199], v150 offset:22528
	ds_read_b128 v[200:203], v150 offset:23552
	global_load_lds_dwordx4 v130, s[20:21]
	s_mov_b32 m0, s31
	s_nop 0
	global_load_lds_dwordx4 v132, s[20:21]
	s_barrier
	s_waitcnt lgkmcnt(0)
	s_setprio 1
	s_waitcnt lgkmcnt(0)
	v_mfma_f32_16x16x32_bf16 v[62:65], v[152:155], v[168:171], 0
	v_mfma_f32_16x16x32_bf16 v[58:61], v[160:163], v[168:171], 0
	v_mfma_f32_16x16x32_bf16 v[50:53], v[152:155], v[180:183], 0
	v_mfma_f32_16x16x32_bf16 v[42:45], v[160:163], v[180:183], 0
	v_mfma_f32_16x16x32_bf16 v[34:37], v[152:155], v[188:191], 0
	v_mfma_f32_16x16x32_bf16 v[26:29], v[160:163], v[188:191], 0
	v_mfma_f32_16x16x32_bf16 v[18:21], v[152:155], v[196:199], 0
	v_mfma_f32_16x16x32_bf16 v[10:13], v[160:163], v[196:199], 0
	v_mfma_f32_16x16x32_bf16 v[62:65], v[156:159], v[172:175], v[62:65]
	v_mfma_f32_16x16x32_bf16 v[58:61], v[164:167], v[172:175], v[58:61]
	v_mfma_f32_16x16x32_bf16 v[50:53], v[156:159], v[184:187], v[50:53]
	v_mfma_f32_16x16x32_bf16 v[42:45], v[164:167], v[184:187], v[42:45]
	v_mfma_f32_16x16x32_bf16 v[34:37], v[156:159], v[192:195], v[34:37]
	v_mfma_f32_16x16x32_bf16 v[26:29], v[164:167], v[192:195], v[26:29]
	v_mfma_f32_16x16x32_bf16 v[18:21], v[156:159], v[200:203], v[18:21]
	v_mfma_f32_16x16x32_bf16 v[10:13], v[164:167], v[200:203], v[10:13]
	s_setprio 0
	s_barrier
	s_add_u32 s56, s18, 0xb0000
	s_addc_u32 s57, s19, 0
	s_add_i32 s55, s42, s27
	s_mov_b32 m0, s55
	s_nop 0
	global_load_lds_dwordx4 v134, s[56:57]
	s_add_i32 m0, s55, 0x2000
	s_nop 0
	global_load_lds_dwordx4 v136, s[56:57]
	s_waitcnt vmcnt(6)
	s_barrier
	s_setprio 1
	v_mfma_f32_16x16x32_bf16 v[54:57], v[206:209], v[168:171], 0
	v_mfma_f32_16x16x32_bf16 v[46:49], v[216:219], v[168:171], 0
	v_mfma_f32_16x16x32_bf16 v[38:41], v[206:209], v[180:183], 0
	v_mfma_f32_16x16x32_bf16 v[30:33], v[216:219], v[180:183], 0
	v_mfma_f32_16x16x32_bf16 v[22:25], v[206:209], v[188:191], 0
	v_mfma_f32_16x16x32_bf16 v[14:17], v[216:219], v[188:191], 0
	v_mfma_f32_16x16x32_bf16 v[6:9], v[206:209], v[196:199], 0
	v_mfma_f32_16x16x32_bf16 v[2:5], v[216:219], v[196:199], 0
	v_mfma_f32_16x16x32_bf16 v[54:57], v[212:215], v[172:175], v[54:57]
	v_mfma_f32_16x16x32_bf16 v[46:49], v[220:223], v[172:175], v[46:49]
	v_mfma_f32_16x16x32_bf16 v[38:41], v[212:215], v[184:187], v[38:41]
	v_mfma_f32_16x16x32_bf16 v[30:33], v[220:223], v[184:187], v[30:33]
	v_mfma_f32_16x16x32_bf16 v[22:25], v[212:215], v[192:195], v[22:25]
	v_mfma_f32_16x16x32_bf16 v[14:17], v[220:223], v[192:195], v[14:17]
	v_mfma_f32_16x16x32_bf16 v[6:9], v[212:215], v[200:203], v[6:9]
	v_mfma_f32_16x16x32_bf16 v[2:5], v[220:223], v[200:203], v[2:5]
	s_setprio 0
	s_add_i32 s55, 0, 0x18000
	v_add_u32_e32 v164, s55, v148
	s_barrier
	ds_read_b128 v[152:155], v164
	ds_read_b128 v[156:159], v164 offset:1024
	ds_read_b128 v[160:163], v164 offset:2048
	ds_read_b128 v[164:167], v164 offset:3072
	s_add_u32 s20, s20, 0xb0000
	s_addc_u32 s21, s21, 0
	s_mov_b32 m0, s33
	ds_read_b128 v[168:171], v150 offset:32768
	ds_read_b128 v[172:175], v150 offset:33792
	ds_read_b128 v[180:183], v150 offset:34816
	ds_read_b128 v[184:187], v150 offset:35840
	ds_read_b128 v[188:191], v150 offset:36864
	ds_read_b128 v[192:195], v150 offset:37888
	ds_read_b128 v[196:199], v150 offset:38912
	ds_read_b128 v[200:203], v150 offset:39936
	global_load_lds_dwordx4 v130, s[20:21]
	s_mov_b32 m0, s34
	s_nop 0
	global_load_lds_dwordx4 v132, s[20:21]
	s_waitcnt lgkmcnt(8)
	s_barrier
	s_waitcnt lgkmcnt(0)
	s_setprio 1
	s_waitcnt lgkmcnt(0)
	v_mfma_f32_16x16x32_bf16 v[126:129], v[152:155], v[168:171], v[126:129]
	v_mfma_f32_16x16x32_bf16 v[122:125], v[160:163], v[168:171], v[122:125]
	v_mfma_f32_16x16x32_bf16 v[114:117], v[152:155], v[180:183], v[114:117]
	v_mfma_f32_16x16x32_bf16 v[106:109], v[160:163], v[180:183], v[106:109]
	v_mfma_f32_16x16x32_bf16 v[98:101], v[152:155], v[188:191], v[98:101]
	v_mfma_f32_16x16x32_bf16 v[90:93], v[160:163], v[188:191], v[90:93]
	v_mfma_f32_16x16x32_bf16 v[82:85], v[152:155], v[196:199], v[82:85]
	v_mfma_f32_16x16x32_bf16 v[74:77], v[160:163], v[196:199], v[74:77]
	v_mfma_f32_16x16x32_bf16 v[126:129], v[156:159], v[172:175], v[126:129]
	v_mfma_f32_16x16x32_bf16 v[122:125], v[164:167], v[172:175], v[122:125]
	v_mfma_f32_16x16x32_bf16 v[114:117], v[156:159], v[184:187], v[114:117]
	v_mfma_f32_16x16x32_bf16 v[106:109], v[164:167], v[184:187], v[106:109]
	v_mfma_f32_16x16x32_bf16 v[98:101], v[156:159], v[192:195], v[98:101]
	v_mfma_f32_16x16x32_bf16 v[90:93], v[164:167], v[192:195], v[90:93]
	v_mfma_f32_16x16x32_bf16 v[82:85], v[156:159], v[200:203], v[82:85]
	v_mfma_f32_16x16x32_bf16 v[74:77], v[164:167], v[200:203], v[74:77]
	s_setprio 0
	s_barrier
	s_add_i32 s20, 0, 0x1c000
	s_add_i32 s21, s55, s27
	v_add_u32_e32 v179, s20, v148
	s_mov_b32 m0, s21
	ds_read_b128 v[206:209], v179
	ds_read_b128 v[212:215], v179 offset:1024
	ds_read_b128 v[216:219], v179 offset:2048
	ds_read_b128 v[220:223], v179 offset:3072
	global_load_lds_dwordx4 v134, s[98:99]
	s_add_i32 m0, s21, 0x2000
	s_nop 0
	global_load_lds_dwordx4 v136, s[98:99]
	s_barrier
	s_waitcnt lgkmcnt(0)
	s_setprio 1
	s_waitcnt lgkmcnt(0)
	v_mfma_f32_16x16x32_bf16 v[118:121], v[206:209], v[168:171], v[118:121]
	v_mfma_f32_16x16x32_bf16 v[110:113], v[216:219], v[168:171], v[110:113]
	v_mfma_f32_16x16x32_bf16 v[102:105], v[206:209], v[180:183], v[102:105]
	v_mfma_f32_16x16x32_bf16 v[94:97], v[216:219], v[180:183], v[94:97]
	v_mfma_f32_16x16x32_bf16 v[86:89], v[206:209], v[188:191], v[86:89]
	v_mfma_f32_16x16x32_bf16 v[78:81], v[216:219], v[188:191], v[78:81]
	v_mfma_f32_16x16x32_bf16 v[70:73], v[206:209], v[196:199], v[70:73]
	v_mfma_f32_16x16x32_bf16 v[66:69], v[216:219], v[196:199], v[66:69]
	v_mfma_f32_16x16x32_bf16 v[118:121], v[212:215], v[172:175], v[118:121]
	v_mfma_f32_16x16x32_bf16 v[110:113], v[220:223], v[172:175], v[110:113]
	v_mfma_f32_16x16x32_bf16 v[102:105], v[212:215], v[184:187], v[102:105]
	v_mfma_f32_16x16x32_bf16 v[94:97], v[220:223], v[184:187], v[94:97]
	v_mfma_f32_16x16x32_bf16 v[86:89], v[212:215], v[192:195], v[86:89]
	v_mfma_f32_16x16x32_bf16 v[78:81], v[220:223], v[192:195], v[78:81]
	v_mfma_f32_16x16x32_bf16 v[70:73], v[212:215], v[200:203], v[70:73]
	v_mfma_f32_16x16x32_bf16 v[66:69], v[220:223], v[200:203], v[66:69]
	s_setprio 0
	s_mov_b32 m0, s37
	s_barrier
	ds_read_b128 v[168:171], v150 offset:49152
	ds_read_b128 v[172:175], v150 offset:50176
	ds_read_b128 v[180:183], v150 offset:51200
	ds_read_b128 v[184:187], v150 offset:52224
	ds_read_b128 v[188:191], v150 offset:53248
	ds_read_b128 v[192:195], v150 offset:54272
	ds_read_b128 v[196:199], v150 offset:55296
	ds_read_b128 v[200:203], v150 offset:56320
	global_load_lds_dwordx4 v130, s[100:101]
	s_mov_b32 m0, s38
	s_nop 0
	global_load_lds_dwordx4 v132, s[100:101]
	s_barrier
	s_waitcnt lgkmcnt(0)
	s_setprio 1
	s_waitcnt lgkmcnt(0)
	v_mfma_f32_16x16x32_bf16 v[62:65], v[152:155], v[168:171], v[62:65]
	v_mfma_f32_16x16x32_bf16 v[58:61], v[160:163], v[168:171], v[58:61]
	v_mfma_f32_16x16x32_bf16 v[50:53], v[152:155], v[180:183], v[50:53]
	v_mfma_f32_16x16x32_bf16 v[42:45], v[160:163], v[180:183], v[42:45]
	v_mfma_f32_16x16x32_bf16 v[34:37], v[152:155], v[188:191], v[34:37]
	v_mfma_f32_16x16x32_bf16 v[26:29], v[160:163], v[188:191], v[26:29]
	v_mfma_f32_16x16x32_bf16 v[18:21], v[152:155], v[196:199], v[18:21]
	v_mfma_f32_16x16x32_bf16 v[10:13], v[160:163], v[196:199], v[10:13]
	v_mfma_f32_16x16x32_bf16 v[62:65], v[156:159], v[172:175], v[62:65]
	v_mfma_f32_16x16x32_bf16 v[58:61], v[164:167], v[172:175], v[58:61]
	v_mfma_f32_16x16x32_bf16 v[50:53], v[156:159], v[184:187], v[50:53]
	v_mfma_f32_16x16x32_bf16 v[42:45], v[164:167], v[184:187], v[42:45]
	v_mfma_f32_16x16x32_bf16 v[34:37], v[156:159], v[192:195], v[34:37]
	v_mfma_f32_16x16x32_bf16 v[26:29], v[164:167], v[192:195], v[26:29]
	v_mfma_f32_16x16x32_bf16 v[18:21], v[156:159], v[200:203], v[18:21]
	v_mfma_f32_16x16x32_bf16 v[10:13], v[164:167], v[200:203], v[10:13]
	s_setprio 0
	s_barrier
	s_add_u32 s18, s18, 0xb0080
	s_addc_u32 s19, s19, 0
	s_add_i32 s20, s20, s27
	s_mov_b32 m0, s20
	s_nop 0
	global_load_lds_dwordx4 v134, s[18:19]
	s_add_i32 m0, s20, 0x2000
	s_nop 0
	global_load_lds_dwordx4 v136, s[18:19]
	s_waitcnt vmcnt(6)
	s_barrier
	s_setprio 1
	v_mfma_f32_16x16x32_bf16 v[54:57], v[206:209], v[168:171], v[54:57]
	v_mfma_f32_16x16x32_bf16 v[46:49], v[216:219], v[168:171], v[46:49]
	v_mfma_f32_16x16x32_bf16 v[38:41], v[206:209], v[180:183], v[38:41]
	v_mfma_f32_16x16x32_bf16 v[30:33], v[216:219], v[180:183], v[30:33]
	v_mfma_f32_16x16x32_bf16 v[22:25], v[206:209], v[188:191], v[22:25]
	v_mfma_f32_16x16x32_bf16 v[14:17], v[216:219], v[188:191], v[14:17]
	v_mfma_f32_16x16x32_bf16 v[6:9], v[206:209], v[196:199], v[6:9]
	v_mfma_f32_16x16x32_bf16 v[2:5], v[216:219], v[196:199], v[2:5]
	v_mfma_f32_16x16x32_bf16 v[54:57], v[212:215], v[172:175], v[54:57]
	v_mfma_f32_16x16x32_bf16 v[46:49], v[220:223], v[172:175], v[46:49]
	v_mfma_f32_16x16x32_bf16 v[38:41], v[212:215], v[184:187], v[38:41]
	v_mfma_f32_16x16x32_bf16 v[30:33], v[220:223], v[184:187], v[30:33]
	v_mfma_f32_16x16x32_bf16 v[22:25], v[212:215], v[192:195], v[22:25]
	v_mfma_f32_16x16x32_bf16 v[14:17], v[220:223], v[192:195], v[14:17]
	v_mfma_f32_16x16x32_bf16 v[6:9], v[212:215], v[200:203], v[6:9]
	v_mfma_f32_16x16x32_bf16 v[2:5], v[220:223], v[200:203], v[2:5]
	s_setprio 0
	s_add_i32 s54, s54, 2
	s_add_u32 s16, s16, 0x100
	s_addc_u32 s17, s17, 0
	s_add_u32 s52, s52, 0x100
	s_addc_u32 s53, s53, 0
	s_cmp_gt_u32 s54, 41
	s_barrier
	s_cbranch_scc1 .Lpeel_p10_exit
.LBB0_1197:
	ds_read_b128 v[152:155], v149
	ds_read_b128 v[156:159], v149 offset:1024
	ds_read_b128 v[160:163], v149 offset:2048
	ds_read_b128 v[164:167], v149 offset:3072
	s_add_u32 s18, s16, 0xfff50080
	s_addc_u32 s19, s17, -1
	s_cmp_eq_u32 s54, 40
	s_cselect_b32 s21, s3, s19
	s_cselect_b32 s20, s2, s18
	s_cselect_b32 s19, s5, s53
	s_cselect_b32 s18, s4, s52
	s_add_i32 m0, s30, 0xc000
	ds_read_b128 v[168:171], v150
	ds_read_b128 v[172:175], v150 offset:1024
	ds_read_b128 v[180:183], v150 offset:2048
	ds_read_b128 v[184:187], v150 offset:3072
	ds_read_b128 v[188:191], v150 offset:4096
	ds_read_b128 v[192:195], v150 offset:5120
	ds_read_b128 v[196:199], v150 offset:6144
	ds_read_b128 v[200:203], v150 offset:7168
	global_load_lds_dwordx4 v138, s[16:17]
	s_add_i32 m0, s30, 0xe000
	s_nop 0
	global_load_lds_dwordx4 v140, s[16:17]
	s_waitcnt lgkmcnt(8)
	s_barrier
	s_waitcnt lgkmcnt(0)
	s_setprio 1
	s_waitcnt lgkmcnt(0)
	v_mfma_f32_16x16x32_bf16 v[126:129], v[152:155], v[168:171], v[126:129]
	v_mfma_f32_16x16x32_bf16 v[122:125], v[160:163], v[168:171], v[122:125]
	v_mfma_f32_16x16x32_bf16 v[114:117], v[152:155], v[180:183], v[114:117]
	v_mfma_f32_16x16x32_bf16 v[106:109], v[160:163], v[180:183], v[106:109]
	v_mfma_f32_16x16x32_bf16 v[98:101], v[152:155], v[188:191], v[98:101]
	v_mfma_f32_16x16x32_bf16 v[90:93], v[160:163], v[188:191], v[90:93]
	v_mfma_f32_16x16x32_bf16 v[82:85], v[152:155], v[196:199], v[82:85]
	v_mfma_f32_16x16x32_bf16 v[74:77], v[160:163], v[196:199], v[74:77]
	v_mfma_f32_16x16x32_bf16 v[126:129], v[156:159], v[172:175], v[126:129]
	v_mfma_f32_16x16x32_bf16 v[122:125], v[164:167], v[172:175], v[122:125]
	v_mfma_f32_16x16x32_bf16 v[114:117], v[156:159], v[184:187], v[114:117]
	v_mfma_f32_16x16x32_bf16 v[106:109], v[164:167], v[184:187], v[106:109]
	v_mfma_f32_16x16x32_bf16 v[98:101], v[156:159], v[192:195], v[98:101]
	v_mfma_f32_16x16x32_bf16 v[90:93], v[164:167], v[192:195], v[90:93]
	v_mfma_f32_16x16x32_bf16 v[82:85], v[156:159], v[200:203], v[82:85]
	v_mfma_f32_16x16x32_bf16 v[74:77], v[164:167], v[200:203], v[74:77]
	s_setprio 0
	s_barrier
	s_add_i32 s55, s41, s27
	s_add_u32 s98, s18, 0x80
	s_addc_u32 s99, s19, 0
	s_mov_b32 m0, s55
	ds_read_b128 v[206:209], v151
	ds_read_b128 v[212:215], v151 offset:1024
	ds_read_b128 v[216:219], v151 offset:2048
	ds_read_b128 v[220:223], v151 offset:3072
	global_load_lds_dwordx4 v134, s[18:19]
	s_add_i32 m0, s55, 0x2000
	s_nop 0
	global_load_lds_dwordx4 v136, s[18:19]
	s_barrier
	s_waitcnt lgkmcnt(0)
	s_setprio 1
	s_waitcnt lgkmcnt(0)
	v_mfma_f32_16x16x32_bf16 v[118:121], v[206:209], v[168:171], v[118:121]
	v_mfma_f32_16x16x32_bf16 v[110:113], v[216:219], v[168:171], v[110:113]
	v_mfma_f32_16x16x32_bf16 v[102:105], v[206:209], v[180:183], v[102:105]
	v_mfma_f32_16x16x32_bf16 v[94:97], v[216:219], v[180:183], v[94:97]
	v_mfma_f32_16x16x32_bf16 v[86:89], v[206:209], v[188:191], v[86:89]
	v_mfma_f32_16x16x32_bf16 v[78:81], v[216:219], v[188:191], v[78:81]
	v_mfma_f32_16x16x32_bf16 v[70:73], v[206:209], v[196:199], v[70:73]
	v_mfma_f32_16x16x32_bf16 v[66:69], v[216:219], v[196:199], v[66:69]
	v_mfma_f32_16x16x32_bf16 v[118:121], v[212:215], v[172:175], v[118:121]
	v_mfma_f32_16x16x32_bf16 v[110:113], v[220:223], v[172:175], v[110:113]
	v_mfma_f32_16x16x32_bf16 v[102:105], v[212:215], v[184:187], v[102:105]
	v_mfma_f32_16x16x32_bf16 v[94:97], v[220:223], v[184:187], v[94:97]
	v_mfma_f32_16x16x32_bf16 v[86:89], v[212:215], v[192:195], v[86:89]
	v_mfma_f32_16x16x32_bf16 v[78:81], v[220:223], v[192:195], v[78:81]
	v_mfma_f32_16x16x32_bf16 v[70:73], v[212:215], v[200:203], v[70:73]
	v_mfma_f32_16x16x32_bf16 v[66:69], v[220:223], v[200:203], v[66:69]
	s_setprio 0
	s_mov_b32 m0, s30
	s_add_u32 s100, s20, 0x80
	s_addc_u32 s101, s21, 0
	s_barrier
	ds_read_b128 v[168:171], v150 offset:16384
	ds_read_b128 v[172:175], v150 offset:17408
	ds_read_b128 v[180:183], v150 offset:18432
	ds_read_b128 v[184:187], v150 offset:19456
	ds_read_b128 v[188:191], v150 offset:20480
	ds_read_b128 v[192:195], v150 offset:21504
	ds_read_b128 v[196:199], v150 offset:22528
	ds_read_b128 v[200:203], v150 offset:23552
	global_load_lds_dwordx4 v130, s[20:21]
	s_mov_b32 m0, s31
	s_nop 0
	global_load_lds_dwordx4 v132, s[20:21]
	s_barrier
	s_waitcnt lgkmcnt(0)
	s_setprio 1
	s_waitcnt lgkmcnt(0)
	v_mfma_f32_16x16x32_bf16 v[62:65], v[152:155], v[168:171], v[62:65]
	v_mfma_f32_16x16x32_bf16 v[58:61], v[160:163], v[168:171], v[58:61]
	v_mfma_f32_16x16x32_bf16 v[50:53], v[152:155], v[180:183], v[50:53]
	v_mfma_f32_16x16x32_bf16 v[42:45], v[160:163], v[180:183], v[42:45]
	v_mfma_f32_16x16x32_bf16 v[34:37], v[152:155], v[188:191], v[34:37]
	v_mfma_f32_16x16x32_bf16 v[26:29], v[160:163], v[188:191], v[26:29]
	v_mfma_f32_16x16x32_bf16 v[18:21], v[152:155], v[196:199], v[18:21]
	v_mfma_f32_16x16x32_bf16 v[10:13], v[160:163], v[196:199], v[10:13]
	v_mfma_f32_16x16x32_bf16 v[62:65], v[156:159], v[172:175], v[62:65]
	v_mfma_f32_16x16x32_bf16 v[58:61], v[164:167], v[172:175], v[58:61]
	v_mfma_f32_16x16x32_bf16 v[50:53], v[156:159], v[184:187], v[50:53]
	v_mfma_f32_16x16x32_bf16 v[42:45], v[164:167], v[184:187], v[42:45]
	v_mfma_f32_16x16x32_bf16 v[34:37], v[156:159], v[192:195], v[34:37]
	v_mfma_f32_16x16x32_bf16 v[26:29], v[164:167], v[192:195], v[26:29]
	v_mfma_f32_16x16x32_bf16 v[18:21], v[156:159], v[200:203], v[18:21]
	v_mfma_f32_16x16x32_bf16 v[10:13], v[164:167], v[200:203], v[10:13]
	s_setprio 0
	s_barrier
	s_add_u32 s56, s18, 0xb0000
	s_addc_u32 s57, s19, 0
	s_add_i32 s55, s42, s27
	s_mov_b32 m0, s55
	s_nop 0
	global_load_lds_dwordx4 v134, s[56:57]
	s_add_i32 m0, s55, 0x2000
	s_nop 0
	global_load_lds_dwordx4 v136, s[56:57]
	s_waitcnt vmcnt(6)
	s_barrier
	s_setprio 1
	v_mfma_f32_16x16x32_bf16 v[54:57], v[206:209], v[168:171], v[54:57]
	v_mfma_f32_16x16x32_bf16 v[46:49], v[216:219], v[168:171], v[46:49]
	v_mfma_f32_16x16x32_bf16 v[38:41], v[206:209], v[180:183], v[38:41]
	v_mfma_f32_16x16x32_bf16 v[30:33], v[216:219], v[180:183], v[30:33]
	v_mfma_f32_16x16x32_bf16 v[22:25], v[206:209], v[188:191], v[22:25]
	v_mfma_f32_16x16x32_bf16 v[14:17], v[216:219], v[188:191], v[14:17]
	v_mfma_f32_16x16x32_bf16 v[6:9], v[206:209], v[196:199], v[6:9]
	v_mfma_f32_16x16x32_bf16 v[2:5], v[216:219], v[196:199], v[2:5]
	v_mfma_f32_16x16x32_bf16 v[54:57], v[212:215], v[172:175], v[54:57]
	v_mfma_f32_16x16x32_bf16 v[46:49], v[220:223], v[172:175], v[46:49]
	v_mfma_f32_16x16x32_bf16 v[38:41], v[212:215], v[184:187], v[38:41]
	v_mfma_f32_16x16x32_bf16 v[30:33], v[220:223], v[184:187], v[30:33]
	v_mfma_f32_16x16x32_bf16 v[22:25], v[212:215], v[192:195], v[22:25]
	v_mfma_f32_16x16x32_bf16 v[14:17], v[220:223], v[192:195], v[14:17]
	v_mfma_f32_16x16x32_bf16 v[6:9], v[212:215], v[200:203], v[6:9]
	v_mfma_f32_16x16x32_bf16 v[2:5], v[220:223], v[200:203], v[2:5]
	s_setprio 0
	s_add_i32 s55, 0, 0x18000
	v_add_u32_e32 v164, s55, v148
	s_barrier
	ds_read_b128 v[152:155], v164
	ds_read_b128 v[156:159], v164 offset:1024
	ds_read_b128 v[160:163], v164 offset:2048
	ds_read_b128 v[164:167], v164 offset:3072
	s_add_u32 s20, s20, 0xb0000
	s_addc_u32 s21, s21, 0
	s_mov_b32 m0, s33
	ds_read_b128 v[168:171], v150 offset:32768
	ds_read_b128 v[172:175], v150 offset:33792
	ds_read_b128 v[180:183], v150 offset:34816
	ds_read_b128 v[184:187], v150 offset:35840
	ds_read_b128 v[188:191], v150 offset:36864
	ds_read_b128 v[192:195], v150 offset:37888
	ds_read_b128 v[196:199], v150 offset:38912
	ds_read_b128 v[200:203], v150 offset:39936
	global_load_lds_dwordx4 v130, s[20:21]
	s_mov_b32 m0, s34
	s_nop 0
	global_load_lds_dwordx4 v132, s[20:21]
	s_waitcnt lgkmcnt(8)
	s_barrier
	s_waitcnt lgkmcnt(0)
	s_setprio 1
	s_waitcnt lgkmcnt(0)
	v_mfma_f32_16x16x32_bf16 v[126:129], v[152:155], v[168:171], v[126:129]
	v_mfma_f32_16x16x32_bf16 v[122:125], v[160:163], v[168:171], v[122:125]
	v_mfma_f32_16x16x32_bf16 v[114:117], v[152:155], v[180:183], v[114:117]
	v_mfma_f32_16x16x32_bf16 v[106:109], v[160:163], v[180:183], v[106:109]
	v_mfma_f32_16x16x32_bf16 v[98:101], v[152:155], v[188:191], v[98:101]
	v_mfma_f32_16x16x32_bf16 v[90:93], v[160:163], v[188:191], v[90:93]
	v_mfma_f32_16x16x32_bf16 v[82:85], v[152:155], v[196:199], v[82:85]
	v_mfma_f32_16x16x32_bf16 v[74:77], v[160:163], v[196:199], v[74:77]
	v_mfma_f32_16x16x32_bf16 v[126:129], v[156:159], v[172:175], v[126:129]
	v_mfma_f32_16x16x32_bf16 v[122:125], v[164:167], v[172:175], v[122:125]
	v_mfma_f32_16x16x32_bf16 v[114:117], v[156:159], v[184:187], v[114:117]
	v_mfma_f32_16x16x32_bf16 v[106:109], v[164:167], v[184:187], v[106:109]
	v_mfma_f32_16x16x32_bf16 v[98:101], v[156:159], v[192:195], v[98:101]
	v_mfma_f32_16x16x32_bf16 v[90:93], v[164:167], v[192:195], v[90:93]
	v_mfma_f32_16x16x32_bf16 v[82:85], v[156:159], v[200:203], v[82:85]
	v_mfma_f32_16x16x32_bf16 v[74:77], v[164:167], v[200:203], v[74:77]
	s_setprio 0
	s_barrier
	s_add_i32 s20, 0, 0x1c000
	s_add_i32 s21, s55, s27
	v_add_u32_e32 v179, s20, v148
	s_mov_b32 m0, s21
	ds_read_b128 v[206:209], v179
	ds_read_b128 v[212:215], v179 offset:1024
	ds_read_b128 v[216:219], v179 offset:2048
	ds_read_b128 v[220:223], v179 offset:3072
	global_load_lds_dwordx4 v134, s[98:99]
	s_add_i32 m0, s21, 0x2000
	s_nop 0
	global_load_lds_dwordx4 v136, s[98:99]
	s_barrier
	s_waitcnt lgkmcnt(0)
	s_setprio 1
	s_waitcnt lgkmcnt(0)
	v_mfma_f32_16x16x32_bf16 v[118:121], v[206:209], v[168:171], v[118:121]
	v_mfma_f32_16x16x32_bf16 v[110:113], v[216:219], v[168:171], v[110:113]
	v_mfma_f32_16x16x32_bf16 v[102:105], v[206:209], v[180:183], v[102:105]
	v_mfma_f32_16x16x32_bf16 v[94:97], v[216:219], v[180:183], v[94:97]
	v_mfma_f32_16x16x32_bf16 v[86:89], v[206:209], v[188:191], v[86:89]
	v_mfma_f32_16x16x32_bf16 v[78:81], v[216:219], v[188:191], v[78:81]
	v_mfma_f32_16x16x32_bf16 v[70:73], v[206:209], v[196:199], v[70:73]
	v_mfma_f32_16x16x32_bf16 v[66:69], v[216:219], v[196:199], v[66:69]
	v_mfma_f32_16x16x32_bf16 v[118:121], v[212:215], v[172:175], v[118:121]
	v_mfma_f32_16x16x32_bf16 v[110:113], v[220:223], v[172:175], v[110:113]
	v_mfma_f32_16x16x32_bf16 v[102:105], v[212:215], v[184:187], v[102:105]
	v_mfma_f32_16x16x32_bf16 v[94:97], v[220:223], v[184:187], v[94:97]
	v_mfma_f32_16x16x32_bf16 v[86:89], v[212:215], v[192:195], v[86:89]
	v_mfma_f32_16x16x32_bf16 v[78:81], v[220:223], v[192:195], v[78:81]
	v_mfma_f32_16x16x32_bf16 v[70:73], v[212:215], v[200:203], v[70:73]
	v_mfma_f32_16x16x32_bf16 v[66:69], v[220:223], v[200:203], v[66:69]
	s_setprio 0
	s_mov_b32 m0, s37
	s_barrier
	ds_read_b128 v[168:171], v150 offset:49152
	ds_read_b128 v[172:175], v150 offset:50176
	ds_read_b128 v[180:183], v150 offset:51200
	ds_read_b128 v[184:187], v150 offset:52224
	ds_read_b128 v[188:191], v150 offset:53248
	ds_read_b128 v[192:195], v150 offset:54272
	ds_read_b128 v[196:199], v150 offset:55296
	ds_read_b128 v[200:203], v150 offset:56320
	global_load_lds_dwordx4 v130, s[100:101]
	s_mov_b32 m0, s38
	s_nop 0
	global_load_lds_dwordx4 v132, s[100:101]
	s_barrier
	s_waitcnt lgkmcnt(0)
	s_setprio 1
	s_waitcnt lgkmcnt(0)
	v_mfma_f32_16x16x32_bf16 v[62:65], v[152:155], v[168:171], v[62:65]
	v_mfma_f32_16x16x32_bf16 v[58:61], v[160:163], v[168:171], v[58:61]
	v_mfma_f32_16x16x32_bf16 v[50:53], v[152:155], v[180:183], v[50:53]
	v_mfma_f32_16x16x32_bf16 v[42:45], v[160:163], v[180:183], v[42:45]
	v_mfma_f32_16x16x32_bf16 v[34:37], v[152:155], v[188:191], v[34:37]
	v_mfma_f32_16x16x32_bf16 v[26:29], v[160:163], v[188:191], v[26:29]
	v_mfma_f32_16x16x32_bf16 v[18:21], v[152:155], v[196:199], v[18:21]
	v_mfma_f32_16x16x32_bf16 v[10:13], v[160:163], v[196:199], v[10:13]
	v_mfma_f32_16x16x32_bf16 v[62:65], v[156:159], v[172:175], v[62:65]
	v_mfma_f32_16x16x32_bf16 v[58:61], v[164:167], v[172:175], v[58:61]
	v_mfma_f32_16x16x32_bf16 v[50:53], v[156:159], v[184:187], v[50:53]
	v_mfma_f32_16x16x32_bf16 v[42:45], v[164:167], v[184:187], v[42:45]
	v_mfma_f32_16x16x32_bf16 v[34:37], v[156:159], v[192:195], v[34:37]
	v_mfma_f32_16x16x32_bf16 v[26:29], v[164:167], v[192:195], v[26:29]
	v_mfma_f32_16x16x32_bf16 v[18:21], v[156:159], v[200:203], v[18:21]
	v_mfma_f32_16x16x32_bf16 v[10:13], v[164:167], v[200:203], v[10:13]
	s_setprio 0
	s_barrier
	s_add_u32 s18, s18, 0xb0080
	s_addc_u32 s19, s19, 0
	s_add_i32 s20, s20, s27
	s_mov_b32 m0, s20
	s_nop 0
	global_load_lds_dwordx4 v134, s[18:19]
	s_add_i32 m0, s20, 0x2000
	s_nop 0
	global_load_lds_dwordx4 v136, s[18:19]
	s_waitcnt vmcnt(6)
	s_barrier
	s_setprio 1
	v_mfma_f32_16x16x32_bf16 v[54:57], v[206:209], v[168:171], v[54:57]
	v_mfma_f32_16x16x32_bf16 v[46:49], v[216:219], v[168:171], v[46:49]
	v_mfma_f32_16x16x32_bf16 v[38:41], v[206:209], v[180:183], v[38:41]
	v_mfma_f32_16x16x32_bf16 v[30:33], v[216:219], v[180:183], v[30:33]
	v_mfma_f32_16x16x32_bf16 v[22:25], v[206:209], v[188:191], v[22:25]
	v_mfma_f32_16x16x32_bf16 v[14:17], v[216:219], v[188:191], v[14:17]
	v_mfma_f32_16x16x32_bf16 v[6:9], v[206:209], v[196:199], v[6:9]
	v_mfma_f32_16x16x32_bf16 v[2:5], v[216:219], v[196:199], v[2:5]
	v_mfma_f32_16x16x32_bf16 v[54:57], v[212:215], v[172:175], v[54:57]
	v_mfma_f32_16x16x32_bf16 v[46:49], v[220:223], v[172:175], v[46:49]
	v_mfma_f32_16x16x32_bf16 v[38:41], v[212:215], v[184:187], v[38:41]
	v_mfma_f32_16x16x32_bf16 v[30:33], v[220:223], v[184:187], v[30:33]
	v_mfma_f32_16x16x32_bf16 v[22:25], v[212:215], v[192:195], v[22:25]
	v_mfma_f32_16x16x32_bf16 v[14:17], v[220:223], v[192:195], v[14:17]
	v_mfma_f32_16x16x32_bf16 v[6:9], v[212:215], v[200:203], v[6:9]
	v_mfma_f32_16x16x32_bf16 v[2:5], v[220:223], v[200:203], v[2:5]
	s_setprio 0
	s_add_i32 s54, s54, 2
	s_add_u32 s16, s16, 0x100
	s_addc_u32 s17, s17, 0
	s_add_u32 s52, s52, 0x100
	s_addc_u32 s53, s53, 0
	s_cmp_gt_u32 s54, 41
	s_barrier
	s_cbranch_scc0 .LBB0_1197

	.amdhsa_kernel _Z14fwd_megakernel6Params
		.amdhsa_group_segment_fixed_size 0
		.amdhsa_private_segment_fixed_size 0
		.amdhsa_kernarg_size 456
		.amdhsa_user_sgpr_count 2
		.amdhsa_user_sgpr_dispatch_ptr 0
		.amdhsa_user_sgpr_queue_ptr 0
		.amdhsa_user_sgpr_kernarg_segment_ptr 1
		.amdhsa_user_sgpr_dispatch_id 0
		.amdhsa_user_sgpr_kernarg_preload_length 0
		.amdhsa_user_sgpr_kernarg_preload_offset 0
		.amdhsa_user_sgpr_private_segment_size 0
		.amdhsa_uses_dynamic_stack 0
		.amdhsa_enable_private_segment 0
		.amdhsa_system_sgpr_workgroup_id_x 1
		.amdhsa_system_sgpr_workgroup_id_y 0
		.amdhsa_system_sgpr_workgroup_id_z 0
		.amdhsa_system_sgpr_workgroup_info 0
		.amdhsa_system_vgpr_workitem_id 0
		.amdhsa_next_free_vgpr 249
		.amdhsa_next_free_sgpr 102
		.amdhsa_accum_offset 252
		.amdhsa_reserve_vcc 1
		.amdhsa_float_round_mode_32 0
		.amdhsa_float_round_mode_16_64 0
		.amdhsa_float_denorm_mode_32 3
		.amdhsa_float_denorm_mode_16_64 3
		.amdhsa_dx10_clamp 1
		.amdhsa_ieee_mode 1
		.amdhsa_fp16_overflow 0
		.amdhsa_tg_split 0
		.amdhsa_exception_fp_ieee_invalid_op 0
		.amdhsa_exception_fp_denorm_src 0
		.amdhsa_exception_fp_ieee_div_zero 0
		.amdhsa_exception_fp_ieee_overflow 0
		.amdhsa_exception_fp_ieee_underflow 0
		.amdhsa_exception_fp_ieee_inexact 0
		.amdhsa_exception_int_div_zero 0
	.end_amdhsa_kernel

amdhsa.kernels:
  - .agpr_count:     0
    .args:
      - .offset:         0
        .size:           200
        .value_kind:     by_value
      - .offset:         200
        .size:           4
        .value_kind:     hidden_block_count_x
      - .offset:         204
        .size:           4
        .value_kind:     hidden_block_count_y
      - .offset:         208
        .size:           4
        .value_kind:     hidden_block_count_z
      - .offset:         212
        .size:           2
        .value_kind:     hidden_group_size_x
      - .offset:         214
        .size:           2
        .value_kind:     hidden_group_size_y
      - .offset:         216
        .size:           2
        .value_kind:     hidden_group_size_z
      - .offset:         218
        .size:           2
        .value_kind:     hidden_remainder_x
      - .offset:         220
        .size:           2
        .value_kind:     hidden_remainder_y
      - .offset:         222
        .size:           2
        .value_kind:     hidden_remainder_z
      - .offset:         240
        .size:           8
        .value_kind:     hidden_global_offset_x
      - .offset:         248
        .size:           8
        .value_kind:     hidden_global_offset_y
      - .offset:         256
        .size:           8
        .value_kind:     hidden_global_offset_z
      - .offset:         264
        .size:           2
        .value_kind:     hidden_grid_dims
      - .offset:         320
        .size:           4
        .value_kind:     hidden_dynamic_lds_size
    .group_segment_fixed_size: 0
    .kernarg_segment_align: 8
    .kernarg_segment_size: 456
    .language:       OpenCL C
    .language_version:
      - 2
      - 0
    .max_flat_workgroup_size: 512
    .name:           _Z14fwd_megakernel6Params
    .private_segment_fixed_size: 0
    .sgpr_count:     108
    .sgpr_spill_count: 154
    .symbol:         _Z14fwd_megakernel6Params.kd
    .uniform_work_group_size: 1
    .uses_dynamic_stack: false
    .vgpr_count:     249
    .vgpr_spill_count: 0
    .wavefront_size: 64
